# rs_fill batched in WIN/FFI/PLE_1/MERGE_0: all units' partial-sum loads issued first (2 x 16-byte loads per unit), one wait, then reduce
# baseline (speedup 1.0000x reference)
; template <int PH, int SUB> __device__ __forceinline__ void rs_fill(LAS unsigned char* lds, const Epi& E) {
;     ...
;         for (int i = 0; i < 12; ++i) { Unit u; if (!sched_next<PH, SUB>(E.ws, E.layer, i, u)) break;
;             const int r = tidx >> 1, hf = tidx & 1; const size_t row = (size_t)(u.pm * 256 + r); f32x4 a, b;
;             { unsigned* pa = (unsigned*)(ssq + ((size_t)(2 * hf) * T_TOK + row) * 4); unsigned* pb = (unsigned*)(ssq + ((size_t)(2 * hf + 1) * T_TOK + row) * 4);
; #pragma unroll
;               for (int j = 0; j < 4; ++j) { a[j] = __uint_as_float(__hip_atomic_load(pa + j, __ATOMIC_RELAXED, __HIP_MEMORY_SCOPE_AGENT)); b[j] = __uint_as_float(__hip_atomic_load(pb + j, __ATOMIC_RELAXED, __HIP_MEMORY_SCOPE_AGENT)); } }
.LBB0_194:
	v_readlane_b32 s2, v233, 5
	v_readlane_b32 s3, v233, 6
	s_load_dwordx4 s[8:11], s[2:3], 0xc8
	v_mov_b32_e32 v0, v186
	v_readlane_b32 s4, v231, 56
	v_and_b32_e32 v9, 1, v0
	v_ashrrev_i32_e32 v8, 1, v0
	s_waitcnt lgkmcnt(0)
	s_add_u32 s2, s10, 0xa800000
	v_lshlrev_b32_e32 v0, 16, v9
	s_addc_u32 s3, s11, 0
	v_or_b32_e32 v2, 0x8000, v0
	v_mov_b32_e32 v3, v1
	v_cmp_eq_u32_e64 s[6:7], 0, v9
	v_lshl_add_u32 v9, v8, 2, s4
	s_mov_b32 s15, s72
	s_cmpk_gt_i32 s15, 0x57f
	s_cbranch_scc1 .Lrsb_WIN_p2
	s_ashr_i32 s4, s15, 31
	s_lshr_b32 s4, s4, 29
	s_add_i32 s4, s15, s4
	s_ashr_i32 s5, s4, 3
	s_and_b32 s4, s4, -8
	s_sub_i32 s4, s15, s4
	s_lshr_b32 s12, s4, 31
	s_or_b32 s12, s12, 0xb0
	s_mul_i32 s4, s12, s4
	s_add_i32 s4, s4, s5
	s_mul_hi_i32 s5, s4, 0x2e8ba2e9
	s_lshr_b32 s12, s5, 31
	s_ashr_i32 s5, s5, 4
	s_add_i32 s5, s5, s12
	s_lshl_b32 s16, s5, 3
	s_sub_i32 s12, 0x80, s16
	s_min_u32 s17, s12, 8
	s_mulk_i32 s5, 0x58
	s_sub_i32 s4, s4, s5
	s_waitcnt lgkmcnt(0)
	v_cvt_f32_ubyte0_e32 v11, s17
	v_cvt_f32_i32_e32 v10, s4
	v_rcp_iflag_f32_e32 v12, v11
	s_ashr_i32 s5, s4, 30
	s_or_b32 s5, s5, 1
	v_mul_f32_e32 v12, v10, v12
	v_trunc_f32_e32 v12, v12
	v_fma_f32 v10, -v12, v11, v10
	v_cvt_i32_f32_e32 v12, v12
	v_cmp_ge_f32_e64 s[12:13], |v10|, v11
	s_and_b64 s[12:13], s[12:13], exec
	s_cselect_b32 s5, s5, 0
	v_readfirstlane_b32 s12, v12
	s_add_i32 s5, s12, s5
	s_mul_i32 s5, s5, s17
	s_sub_i32 s4, s4, s5
	s_sext_i32_i8 s4, s4
	s_add_i32 s16, s16, s4
	v_lshl_add_u32 v10, s16, 8, v8
	v_ashrrev_i32_e32 v11, 31, v10
	v_lshl_add_u64 v[12:13], v[10:11], 0, v[0:1]
	v_lshl_add_u64 v[10:11], v[10:11], 0, v[2:3]
	v_lshl_add_u64 v[12:13], v[12:13], 4, s[2:3]
	v_lshl_add_u64 v[10:11], v[10:11], 4, s[2:3]
	global_load_dwordx4 v[14:17], v[12:13], off sc1
	global_load_dwordx4 v[18:21], v[10:11], off sc1
	s_add_i32 s15, s15, s56
	s_cmpk_gt_i32 s15, 0x57f
	s_cbranch_scc1 .Lrsb_WIN_p2
	s_ashr_i32 s4, s15, 31
	s_lshr_b32 s4, s4, 29
	s_add_i32 s4, s15, s4
	s_ashr_i32 s5, s4, 3
	s_and_b32 s4, s4, -8
	s_sub_i32 s4, s15, s4
	s_lshr_b32 s12, s4, 31
	s_or_b32 s12, s12, 0xb0
	s_mul_i32 s4, s12, s4
	s_add_i32 s4, s4, s5
	s_mul_hi_i32 s5, s4, 0x2e8ba2e9
	s_lshr_b32 s12, s5, 31
	s_ashr_i32 s5, s5, 4
	s_add_i32 s5, s5, s12
	s_lshl_b32 s16, s5, 3
	s_sub_i32 s12, 0x80, s16
	s_min_u32 s17, s12, 8
	s_mulk_i32 s5, 0x58
	s_sub_i32 s4, s4, s5
	s_waitcnt lgkmcnt(0)
	v_cvt_f32_ubyte0_e32 v11, s17
	v_cvt_f32_i32_e32 v10, s4
	v_rcp_iflag_f32_e32 v12, v11
	s_ashr_i32 s5, s4, 30
	s_or_b32 s5, s5, 1
	v_mul_f32_e32 v12, v10, v12
	v_trunc_f32_e32 v12, v12
	v_fma_f32 v10, -v12, v11, v10
	v_cvt_i32_f32_e32 v12, v12
	v_cmp_ge_f32_e64 s[12:13], |v10|, v11
	s_and_b64 s[12:13], s[12:13], exec
	s_cselect_b32 s5, s5, 0
	v_readfirstlane_b32 s12, v12
	s_add_i32 s5, s12, s5
	s_mul_i32 s5, s5, s17
	s_sub_i32 s4, s4, s5
	s_sext_i32_i8 s4, s4
	s_add_i32 s16, s16, s4
	v_lshl_add_u32 v10, s16, 8, v8
	v_ashrrev_i32_e32 v11, 31, v10
	v_lshl_add_u64 v[12:13], v[10:11], 0, v[0:1]
	v_lshl_add_u64 v[10:11], v[10:11], 0, v[2:3]
	v_lshl_add_u64 v[12:13], v[12:13], 4, s[2:3]
	v_lshl_add_u64 v[10:11], v[10:11], 4, s[2:3]
	global_load_dwordx4 v[22:25], v[12:13], off sc1
	global_load_dwordx4 v[26:29], v[10:11], off sc1
	s_add_i32 s15, s15, s56
	s_cmpk_gt_i32 s15, 0x57f
	s_cbranch_scc1 .Lrsb_WIN_p2
	s_ashr_i32 s4, s15, 31
	s_lshr_b32 s4, s4, 29
	s_add_i32 s4, s15, s4
	s_ashr_i32 s5, s4, 3
	s_and_b32 s4, s4, -8
	s_sub_i32 s4, s15, s4
	s_lshr_b32 s12, s4, 31
	s_or_b32 s12, s12, 0xb0
	s_mul_i32 s4, s12, s4
	s_add_i32 s4, s4, s5
	s_mul_hi_i32 s5, s4, 0x2e8ba2e9
	s_lshr_b32 s12, s5, 31
	s_ashr_i32 s5, s5, 4
	s_add_i32 s5, s5, s12
	s_lshl_b32 s16, s5, 3
	s_sub_i32 s12, 0x80, s16
	s_min_u32 s17, s12, 8
	s_mulk_i32 s5, 0x58
	s_sub_i32 s4, s4, s5
	s_waitcnt lgkmcnt(0)
	v_cvt_f32_ubyte0_e32 v11, s17
	v_cvt_f32_i32_e32 v10, s4
	v_rcp_iflag_f32_e32 v12, v11
	s_ashr_i32 s5, s4, 30
	s_or_b32 s5, s5, 1
	v_mul_f32_e32 v12, v10, v12
	v_trunc_f32_e32 v12, v12
	v_fma_f32 v10, -v12, v11, v10
	v_cvt_i32_f32_e32 v12, v12
	v_cmp_ge_f32_e64 s[12:13], |v10|, v11
	s_and_b64 s[12:13], s[12:13], exec
	s_cselect_b32 s5, s5, 0
	v_readfirstlane_b32 s12, v12
	s_add_i32 s5, s12, s5
	s_mul_i32 s5, s5, s17
	s_sub_i32 s4, s4, s5
	s_sext_i32_i8 s4, s4
	s_add_i32 s16, s16, s4
	v_lshl_add_u32 v10, s16, 8, v8
	v_ashrrev_i32_e32 v11, 31, v10
	v_lshl_add_u64 v[12:13], v[10:11], 0, v[0:1]
	v_lshl_add_u64 v[10:11], v[10:11], 0, v[2:3]
	v_lshl_add_u64 v[12:13], v[12:13], 4, s[2:3]
	v_lshl_add_u64 v[10:11], v[10:11], 4, s[2:3]
	global_load_dwordx4 v[30:33], v[12:13], off sc1
	global_load_dwordx4 v[34:37], v[10:11], off sc1
	s_add_i32 s15, s15, s56
	s_cmpk_gt_i32 s15, 0x57f
	s_cbranch_scc1 .Lrsb_WIN_p2
	s_ashr_i32 s4, s15, 31
	s_lshr_b32 s4, s4, 29
	s_add_i32 s4, s15, s4
	s_ashr_i32 s5, s4, 3
	s_and_b32 s4, s4, -8
	s_sub_i32 s4, s15, s4
	s_lshr_b32 s12, s4, 31
	s_or_b32 s12, s12, 0xb0
	s_mul_i32 s4, s12, s4
	s_add_i32 s4, s4, s5
	s_mul_hi_i32 s5, s4, 0x2e8ba2e9
	s_lshr_b32 s12, s5, 31
	s_ashr_i32 s5, s5, 4
	s_add_i32 s5, s5, s12
	s_lshl_b32 s16, s5, 3
	s_sub_i32 s12, 0x80, s16
	s_min_u32 s17, s12, 8
	s_mulk_i32 s5, 0x58
	s_sub_i32 s4, s4, s5
	s_waitcnt lgkmcnt(0)
	v_cvt_f32_ubyte0_e32 v11, s17
	v_cvt_f32_i32_e32 v10, s4
	v_rcp_iflag_f32_e32 v12, v11
	s_ashr_i32 s5, s4, 30
	s_or_b32 s5, s5, 1
	v_mul_f32_e32 v12, v10, v12
	v_trunc_f32_e32 v12, v12
	v_fma_f32 v10, -v12, v11, v10
	v_cvt_i32_f32_e32 v12, v12
	v_cmp_ge_f32_e64 s[12:13], |v10|, v11
	s_and_b64 s[12:13], s[12:13], exec
	s_cselect_b32 s5, s5, 0
	v_readfirstlane_b32 s12, v12
	s_add_i32 s5, s12, s5
	s_mul_i32 s5, s5, s17
	s_sub_i32 s4, s4, s5
	s_sext_i32_i8 s4, s4
	s_add_i32 s16, s16, s4
	v_lshl_add_u32 v10, s16, 8, v8
	v_ashrrev_i32_e32 v11, 31, v10
	v_lshl_add_u64 v[12:13], v[10:11], 0, v[0:1]
	v_lshl_add_u64 v[10:11], v[10:11], 0, v[2:3]
	v_lshl_add_u64 v[12:13], v[12:13], 4, s[2:3]
	v_lshl_add_u64 v[10:11], v[10:11], 4, s[2:3]
	global_load_dwordx4 v[38:41], v[12:13], off sc1
	global_load_dwordx4 v[42:45], v[10:11], off sc1
	s_add_i32 s15, s15, s56
	s_cmpk_gt_i32 s15, 0x57f
	s_cbranch_scc1 .Lrsb_WIN_p2
; template <int PH, int SUB> __device__ __forceinline__ void rs_fill(LAS unsigned char* lds, const Epi& E) {
;     ...
;         for (int i = 0; i < 12; ++i) { Unit u; if (!sched_next<PH, SUB>(E.ws, E.layer, i, u)) break;
;             const int r = tidx >> 1, hf = tidx & 1; const size_t row = (size_t)(u.pm * 256 + r); f32x4 a, b;
;             { unsigned* pa = (unsigned*)(ssq + ((size_t)(2 * hf) * T_TOK + row) * 4); unsigned* pb = (unsigned*)(ssq + ((size_t)(2 * hf + 1) * T_TOK + row) * 4);
; #pragma unroll
;               for (int j = 0; j < 4; ++j) { a[j] = __uint_as_float(__hip_atomic_load(pa + j, __ATOMIC_RELAXED, __HIP_MEMORY_SCOPE_AGENT)); b[j] = __uint_as_float(__hip_atomic_load(pb + j, __ATOMIC_RELAXED, __HIP_MEMORY_SCOPE_AGENT)); } }
	s_ashr_i32 s4, s15, 31
	s_lshr_b32 s4, s4, 29
	s_add_i32 s4, s15, s4
	s_ashr_i32 s5, s4, 3
	s_and_b32 s4, s4, -8
	s_sub_i32 s4, s15, s4
	s_lshr_b32 s12, s4, 31
	s_or_b32 s12, s12, 0xb0
	s_mul_i32 s4, s12, s4
	s_add_i32 s4, s4, s5
	s_mul_hi_i32 s5, s4, 0x2e8ba2e9
	s_lshr_b32 s12, s5, 31
	s_ashr_i32 s5, s5, 4
	s_add_i32 s5, s5, s12
	s_lshl_b32 s16, s5, 3
	s_sub_i32 s12, 0x80, s16
	s_min_u32 s17, s12, 8
	s_mulk_i32 s5, 0x58
	s_sub_i32 s4, s4, s5
	s_waitcnt lgkmcnt(0)
	v_cvt_f32_ubyte0_e32 v11, s17
	v_cvt_f32_i32_e32 v10, s4
	v_rcp_iflag_f32_e32 v12, v11
	s_ashr_i32 s5, s4, 30
	s_or_b32 s5, s5, 1
	v_mul_f32_e32 v12, v10, v12
	v_trunc_f32_e32 v12, v12
	v_fma_f32 v10, -v12, v11, v10
	v_cvt_i32_f32_e32 v12, v12
	v_cmp_ge_f32_e64 s[12:13], |v10|, v11
	s_and_b64 s[12:13], s[12:13], exec
	s_cselect_b32 s5, s5, 0
	v_readfirstlane_b32 s12, v12
	s_add_i32 s5, s12, s5
	s_mul_i32 s5, s5, s17
	s_sub_i32 s4, s4, s5
	s_sext_i32_i8 s4, s4
	s_add_i32 s16, s16, s4
	v_lshl_add_u32 v10, s16, 8, v8
	v_ashrrev_i32_e32 v11, 31, v10
	v_lshl_add_u64 v[12:13], v[10:11], 0, v[0:1]
	v_lshl_add_u64 v[10:11], v[10:11], 0, v[2:3]
	v_lshl_add_u64 v[12:13], v[12:13], 4, s[2:3]
	v_lshl_add_u64 v[10:11], v[10:11], 4, s[2:3]
	global_load_dwordx4 v[46:49], v[12:13], off sc1
	global_load_dwordx4 v[50:53], v[10:11], off sc1
	s_add_i32 s15, s15, s56
	s_cmpk_gt_i32 s15, 0x57f
	s_cbranch_scc1 .Lrsb_WIN_p2
	s_ashr_i32 s4, s15, 31
	s_lshr_b32 s4, s4, 29
	s_add_i32 s4, s15, s4
	s_ashr_i32 s5, s4, 3
	s_and_b32 s4, s4, -8
	s_sub_i32 s4, s15, s4
	s_lshr_b32 s12, s4, 31
	s_or_b32 s12, s12, 0xb0
	s_mul_i32 s4, s12, s4
	s_add_i32 s4, s4, s5
	s_mul_hi_i32 s5, s4, 0x2e8ba2e9
	s_lshr_b32 s12, s5, 31
	s_ashr_i32 s5, s5, 4
	s_add_i32 s5, s5, s12
	s_lshl_b32 s16, s5, 3
	s_sub_i32 s12, 0x80, s16
	s_min_u32 s17, s12, 8
	s_mulk_i32 s5, 0x58
	s_sub_i32 s4, s4, s5
	s_waitcnt lgkmcnt(0)
	v_cvt_f32_ubyte0_e32 v11, s17
	v_cvt_f32_i32_e32 v10, s4
	v_rcp_iflag_f32_e32 v12, v11
	s_ashr_i32 s5, s4, 30
	s_or_b32 s5, s5, 1
	v_mul_f32_e32 v12, v10, v12
	v_trunc_f32_e32 v12, v12
	v_fma_f32 v10, -v12, v11, v10
	v_cvt_i32_f32_e32 v12, v12
	v_cmp_ge_f32_e64 s[12:13], |v10|, v11
	s_and_b64 s[12:13], s[12:13], exec
	s_cselect_b32 s5, s5, 0
	v_readfirstlane_b32 s12, v12
	s_add_i32 s5, s12, s5
	s_mul_i32 s5, s5, s17
	s_sub_i32 s4, s4, s5
	s_sext_i32_i8 s4, s4
	s_add_i32 s16, s16, s4
	v_lshl_add_u32 v10, s16, 8, v8
	v_ashrrev_i32_e32 v11, 31, v10
	v_lshl_add_u64 v[12:13], v[10:11], 0, v[0:1]
	v_lshl_add_u64 v[10:11], v[10:11], 0, v[2:3]
	v_lshl_add_u64 v[12:13], v[12:13], 4, s[2:3]
	v_lshl_add_u64 v[10:11], v[10:11], 4, s[2:3]
	global_load_dwordx4 v[54:57], v[12:13], off sc1
	global_load_dwordx4 v[58:61], v[10:11], off sc1
	s_add_i32 s15, s15, s56
	s_cmpk_gt_i32 s15, 0x57f
	s_cbranch_scc1 .Lrsb_WIN_p2
	s_ashr_i32 s4, s15, 31
	s_lshr_b32 s4, s4, 29
	s_add_i32 s4, s15, s4
	s_ashr_i32 s5, s4, 3
	s_and_b32 s4, s4, -8
	s_sub_i32 s4, s15, s4
	s_lshr_b32 s12, s4, 31
	s_or_b32 s12, s12, 0xb0
	s_mul_i32 s4, s12, s4
	s_add_i32 s4, s4, s5
	s_mul_hi_i32 s5, s4, 0x2e8ba2e9
	s_lshr_b32 s12, s5, 31
	s_ashr_i32 s5, s5, 4
	s_add_i32 s5, s5, s12
	s_lshl_b32 s16, s5, 3
	s_sub_i32 s12, 0x80, s16
	s_min_u32 s17, s12, 8
	s_mulk_i32 s5, 0x58
	s_sub_i32 s4, s4, s5
	s_waitcnt lgkmcnt(0)
	v_cvt_f32_ubyte0_e32 v11, s17
	v_cvt_f32_i32_e32 v10, s4
	v_rcp_iflag_f32_e32 v12, v11
	s_ashr_i32 s5, s4, 30
	s_or_b32 s5, s5, 1
	v_mul_f32_e32 v12, v10, v12
	v_trunc_f32_e32 v12, v12
	v_fma_f32 v10, -v12, v11, v10
	v_cvt_i32_f32_e32 v12, v12
	v_cmp_ge_f32_e64 s[12:13], |v10|, v11
	s_and_b64 s[12:13], s[12:13], exec
	s_cselect_b32 s5, s5, 0
	v_readfirstlane_b32 s12, v12
	s_add_i32 s5, s12, s5
	s_mul_i32 s5, s5, s17
	s_sub_i32 s4, s4, s5
	s_sext_i32_i8 s4, s4
	s_add_i32 s16, s16, s4
	v_lshl_add_u32 v10, s16, 8, v8
	v_ashrrev_i32_e32 v11, 31, v10
	v_lshl_add_u64 v[12:13], v[10:11], 0, v[0:1]
	v_lshl_add_u64 v[10:11], v[10:11], 0, v[2:3]
	v_lshl_add_u64 v[12:13], v[12:13], 4, s[2:3]
	v_lshl_add_u64 v[10:11], v[10:11], 4, s[2:3]
	global_load_dwordx4 v[62:65], v[12:13], off sc1
	global_load_dwordx4 v[66:69], v[10:11], off sc1
	s_add_i32 s15, s15, s56
	s_cmpk_gt_i32 s15, 0x57f
	s_cbranch_scc1 .Lrsb_WIN_p2
	s_ashr_i32 s4, s15, 31
	s_lshr_b32 s4, s4, 29
	s_add_i32 s4, s15, s4
	s_ashr_i32 s5, s4, 3
	s_and_b32 s4, s4, -8
	s_sub_i32 s4, s15, s4
	s_lshr_b32 s12, s4, 31
	s_or_b32 s12, s12, 0xb0
	s_mul_i32 s4, s12, s4
	s_add_i32 s4, s4, s5
	s_mul_hi_i32 s5, s4, 0x2e8ba2e9
	s_lshr_b32 s12, s5, 31
	s_ashr_i32 s5, s5, 4
	s_add_i32 s5, s5, s12
	s_lshl_b32 s16, s5, 3
	s_sub_i32 s12, 0x80, s16
	s_min_u32 s17, s12, 8
	s_mulk_i32 s5, 0x58
	s_sub_i32 s4, s4, s5
	s_waitcnt lgkmcnt(0)
	v_cvt_f32_ubyte0_e32 v11, s17
	v_cvt_f32_i32_e32 v10, s4
	v_rcp_iflag_f32_e32 v12, v11
	s_ashr_i32 s5, s4, 30
	s_or_b32 s5, s5, 1
	v_mul_f32_e32 v12, v10, v12
	v_trunc_f32_e32 v12, v12
	v_fma_f32 v10, -v12, v11, v10
	v_cvt_i32_f32_e32 v12, v12
	v_cmp_ge_f32_e64 s[12:13], |v10|, v11
	s_and_b64 s[12:13], s[12:13], exec
	s_cselect_b32 s5, s5, 0
	v_readfirstlane_b32 s12, v12
	s_add_i32 s5, s12, s5
	s_mul_i32 s5, s5, s17
	s_sub_i32 s4, s4, s5
	s_sext_i32_i8 s4, s4
	s_add_i32 s16, s16, s4
	v_lshl_add_u32 v10, s16, 8, v8
	v_ashrrev_i32_e32 v11, 31, v10
	v_lshl_add_u64 v[12:13], v[10:11], 0, v[0:1]
	v_lshl_add_u64 v[10:11], v[10:11], 0, v[2:3]
	v_lshl_add_u64 v[12:13], v[12:13], 4, s[2:3]
	v_lshl_add_u64 v[10:11], v[10:11], 4, s[2:3]
	global_load_dwordx4 v[70:73], v[12:13], off sc1
	global_load_dwordx4 v[74:77], v[10:11], off sc1
	s_add_i32 s15, s15, s56
	s_cmpk_gt_i32 s15, 0x57f
	s_cbranch_scc1 .Lrsb_WIN_p2
; template <int PH, int SUB> __device__ __forceinline__ void rs_fill(LAS unsigned char* lds, const Epi& E) {
;     ...
;         for (int i = 0; i < 12; ++i) { Unit u; if (!sched_next<PH, SUB>(E.ws, E.layer, i, u)) break;
;             const int r = tidx >> 1, hf = tidx & 1; const size_t row = (size_t)(u.pm * 256 + r); f32x4 a, b;
;             { unsigned* pa = (unsigned*)(ssq + ((size_t)(2 * hf) * T_TOK + row) * 4); unsigned* pb = (unsigned*)(ssq + ((size_t)(2 * hf + 1) * T_TOK + row) * 4);
; #pragma unroll
;               for (int j = 0; j < 4; ++j) { a[j] = __uint_as_float(__hip_atomic_load(pa + j, __ATOMIC_RELAXED, __HIP_MEMORY_SCOPE_AGENT)); b[j] = __uint_as_float(__hip_atomic_load(pb + j, __ATOMIC_RELAXED, __HIP_MEMORY_SCOPE_AGENT)); } }
	s_ashr_i32 s4, s15, 31
	s_lshr_b32 s4, s4, 29
	s_add_i32 s4, s15, s4
	s_ashr_i32 s5, s4, 3
	s_and_b32 s4, s4, -8
	s_sub_i32 s4, s15, s4
	s_lshr_b32 s12, s4, 31
	s_or_b32 s12, s12, 0xb0
	s_mul_i32 s4, s12, s4
	s_add_i32 s4, s4, s5
	s_mul_hi_i32 s5, s4, 0x2e8ba2e9
	s_lshr_b32 s12, s5, 31
	s_ashr_i32 s5, s5, 4
	s_add_i32 s5, s5, s12
	s_lshl_b32 s16, s5, 3
	s_sub_i32 s12, 0x80, s16
	s_min_u32 s17, s12, 8
	s_mulk_i32 s5, 0x58
	s_sub_i32 s4, s4, s5
	s_waitcnt lgkmcnt(0)
	v_cvt_f32_ubyte0_e32 v11, s17
	v_cvt_f32_i32_e32 v10, s4
	v_rcp_iflag_f32_e32 v12, v11
	s_ashr_i32 s5, s4, 30
	s_or_b32 s5, s5, 1
	v_mul_f32_e32 v12, v10, v12
	v_trunc_f32_e32 v12, v12
	v_fma_f32 v10, -v12, v11, v10
	v_cvt_i32_f32_e32 v12, v12
	v_cmp_ge_f32_e64 s[12:13], |v10|, v11
	s_and_b64 s[12:13], s[12:13], exec
	s_cselect_b32 s5, s5, 0
	v_readfirstlane_b32 s12, v12
	s_add_i32 s5, s12, s5
	s_mul_i32 s5, s5, s17
	s_sub_i32 s4, s4, s5
	s_sext_i32_i8 s4, s4
	s_add_i32 s16, s16, s4
	v_lshl_add_u32 v10, s16, 8, v8
	v_ashrrev_i32_e32 v11, 31, v10
	v_lshl_add_u64 v[12:13], v[10:11], 0, v[0:1]
	v_lshl_add_u64 v[10:11], v[10:11], 0, v[2:3]
	v_lshl_add_u64 v[12:13], v[12:13], 4, s[2:3]
	v_lshl_add_u64 v[10:11], v[10:11], 4, s[2:3]
	global_load_dwordx4 v[78:81], v[12:13], off sc1
	global_load_dwordx4 v[82:85], v[10:11], off sc1
	s_add_i32 s15, s15, s56
	s_cmpk_gt_i32 s15, 0x57f
	s_cbranch_scc1 .Lrsb_WIN_p2
	s_ashr_i32 s4, s15, 31
	s_lshr_b32 s4, s4, 29
	s_add_i32 s4, s15, s4
	s_ashr_i32 s5, s4, 3
	s_and_b32 s4, s4, -8
	s_sub_i32 s4, s15, s4
	s_lshr_b32 s12, s4, 31
	s_or_b32 s12, s12, 0xb0
	s_mul_i32 s4, s12, s4
	s_add_i32 s4, s4, s5
	s_mul_hi_i32 s5, s4, 0x2e8ba2e9
	s_lshr_b32 s12, s5, 31
	s_ashr_i32 s5, s5, 4
	s_add_i32 s5, s5, s12
	s_lshl_b32 s16, s5, 3
	s_sub_i32 s12, 0x80, s16
	s_min_u32 s17, s12, 8
	s_mulk_i32 s5, 0x58
	s_sub_i32 s4, s4, s5
	s_waitcnt lgkmcnt(0)
	v_cvt_f32_ubyte0_e32 v11, s17
	v_cvt_f32_i32_e32 v10, s4
	v_rcp_iflag_f32_e32 v12, v11
	s_ashr_i32 s5, s4, 30
	s_or_b32 s5, s5, 1
	v_mul_f32_e32 v12, v10, v12
	v_trunc_f32_e32 v12, v12
	v_fma_f32 v10, -v12, v11, v10
	v_cvt_i32_f32_e32 v12, v12
	v_cmp_ge_f32_e64 s[12:13], |v10|, v11
	s_and_b64 s[12:13], s[12:13], exec
	s_cselect_b32 s5, s5, 0
	v_readfirstlane_b32 s12, v12
	s_add_i32 s5, s12, s5
	s_mul_i32 s5, s5, s17
	s_sub_i32 s4, s4, s5
	s_sext_i32_i8 s4, s4
	s_add_i32 s16, s16, s4
	v_lshl_add_u32 v10, s16, 8, v8
	v_ashrrev_i32_e32 v11, 31, v10
	v_lshl_add_u64 v[12:13], v[10:11], 0, v[0:1]
	v_lshl_add_u64 v[10:11], v[10:11], 0, v[2:3]
	v_lshl_add_u64 v[12:13], v[12:13], 4, s[2:3]
	v_lshl_add_u64 v[10:11], v[10:11], 4, s[2:3]
	global_load_dwordx4 v[86:89], v[12:13], off sc1
	global_load_dwordx4 v[90:93], v[10:11], off sc1
	s_add_i32 s15, s15, s56
	s_cmpk_gt_i32 s15, 0x57f
	s_cbranch_scc1 .Lrsb_WIN_p2
	s_ashr_i32 s4, s15, 31
	s_lshr_b32 s4, s4, 29
	s_add_i32 s4, s15, s4
	s_ashr_i32 s5, s4, 3
	s_and_b32 s4, s4, -8
	s_sub_i32 s4, s15, s4
	s_lshr_b32 s12, s4, 31
	s_or_b32 s12, s12, 0xb0
	s_mul_i32 s4, s12, s4
	s_add_i32 s4, s4, s5
	s_mul_hi_i32 s5, s4, 0x2e8ba2e9
	s_lshr_b32 s12, s5, 31
	s_ashr_i32 s5, s5, 4
	s_add_i32 s5, s5, s12
	s_lshl_b32 s16, s5, 3
	s_sub_i32 s12, 0x80, s16
	s_min_u32 s17, s12, 8
	s_mulk_i32 s5, 0x58
	s_sub_i32 s4, s4, s5
	s_waitcnt lgkmcnt(0)
	v_cvt_f32_ubyte0_e32 v11, s17
	v_cvt_f32_i32_e32 v10, s4
	v_rcp_iflag_f32_e32 v12, v11
	s_ashr_i32 s5, s4, 30
	s_or_b32 s5, s5, 1
	v_mul_f32_e32 v12, v10, v12
	v_trunc_f32_e32 v12, v12
	v_fma_f32 v10, -v12, v11, v10
	v_cvt_i32_f32_e32 v12, v12
	v_cmp_ge_f32_e64 s[12:13], |v10|, v11
	s_and_b64 s[12:13], s[12:13], exec
	s_cselect_b32 s5, s5, 0
	v_readfirstlane_b32 s12, v12
	s_add_i32 s5, s12, s5
	s_mul_i32 s5, s5, s17
	s_sub_i32 s4, s4, s5
	s_sext_i32_i8 s4, s4
	s_add_i32 s16, s16, s4
	v_lshl_add_u32 v10, s16, 8, v8
	v_ashrrev_i32_e32 v11, 31, v10
	v_lshl_add_u64 v[12:13], v[10:11], 0, v[0:1]
	v_lshl_add_u64 v[10:11], v[10:11], 0, v[2:3]
	v_lshl_add_u64 v[12:13], v[12:13], 4, s[2:3]
	v_lshl_add_u64 v[10:11], v[10:11], 4, s[2:3]
	global_load_dwordx4 v[94:97], v[12:13], off sc1
	global_load_dwordx4 v[98:101], v[10:11], off sc1
	s_add_i32 s15, s15, s56
	s_cmpk_gt_i32 s15, 0x57f
	s_cbranch_scc1 .Lrsb_WIN_p2
	s_ashr_i32 s4, s15, 31
	s_lshr_b32 s4, s4, 29
	s_add_i32 s4, s15, s4
	s_ashr_i32 s5, s4, 3
	s_and_b32 s4, s4, -8
	s_sub_i32 s4, s15, s4
	s_lshr_b32 s12, s4, 31
	s_or_b32 s12, s12, 0xb0
	s_mul_i32 s4, s12, s4
	s_add_i32 s4, s4, s5
	s_mul_hi_i32 s5, s4, 0x2e8ba2e9
	s_lshr_b32 s12, s5, 31
	s_ashr_i32 s5, s5, 4
	s_add_i32 s5, s5, s12
	s_lshl_b32 s16, s5, 3
	s_sub_i32 s12, 0x80, s16
	s_min_u32 s17, s12, 8
	s_mulk_i32 s5, 0x58
	s_sub_i32 s4, s4, s5
	s_waitcnt lgkmcnt(0)
	v_cvt_f32_ubyte0_e32 v11, s17
	v_cvt_f32_i32_e32 v10, s4
	v_rcp_iflag_f32_e32 v12, v11
	s_ashr_i32 s5, s4, 30
	s_or_b32 s5, s5, 1
	v_mul_f32_e32 v12, v10, v12
	v_trunc_f32_e32 v12, v12
	v_fma_f32 v10, -v12, v11, v10
	v_cvt_i32_f32_e32 v12, v12
	v_cmp_ge_f32_e64 s[12:13], |v10|, v11
	s_and_b64 s[12:13], s[12:13], exec
	s_cselect_b32 s5, s5, 0
	v_readfirstlane_b32 s12, v12
	s_add_i32 s5, s12, s5
	s_mul_i32 s5, s5, s17
	s_sub_i32 s4, s4, s5
	s_sext_i32_i8 s4, s4
	s_add_i32 s16, s16, s4
	v_lshl_add_u32 v10, s16, 8, v8
	v_ashrrev_i32_e32 v11, 31, v10
	v_lshl_add_u64 v[12:13], v[10:11], 0, v[0:1]
	v_lshl_add_u64 v[10:11], v[10:11], 0, v[2:3]
	v_lshl_add_u64 v[12:13], v[12:13], 4, s[2:3]
	v_lshl_add_u64 v[10:11], v[10:11], 4, s[2:3]
	global_load_dwordx4 v[102:105], v[12:13], off sc1
	global_load_dwordx4 v[106:109], v[10:11], off sc1
	s_add_i32 s15, s15, s56
; template <int PH, int SUB> __device__ __forceinline__ void rs_fill(LAS unsigned char* lds, const Epi& E) {
;     ...
;             float t = ((a[0] + a[1]) + (a[2] + a[3])) + ((b[0] + b[1]) + (b[2] + b[3])); t += __shfl_xor(t, 1);
;             if (hf == 0) tab[u.ord * 256 + r] = rsqrtf(t * (1.0f / 1024.0f) + 1e-6f); }
;         __syncthreads();
.Lrsb_WIN_p2:
	v_cmp_lt_i32_e32 vcc, v191, v192
	s_nop 1
	v_cndmask_b32_e32 v11, v190, v191, vcc
	v_lshlrev_b32_e32 v11, 2, v11
	s_waitcnt vmcnt(0)
	v_add_f32_e32 v14, v14, v15
	v_add_f32_e32 v18, v18, v19
	v_add_f32_e32 v16, v16, v17
	v_add_f32_e32 v20, v20, v21
	v_add_f32_e32 v14, v14, v16
	v_add_f32_e32 v18, v18, v20
	v_add_f32_e32 v14, v14, v18
	v_add_f32_e32 v22, v22, v23
	v_add_f32_e32 v26, v26, v27
	v_add_f32_e32 v24, v24, v25
	v_add_f32_e32 v28, v28, v29
	v_add_f32_e32 v22, v22, v24
	v_add_f32_e32 v26, v26, v28
	v_add_f32_e32 v22, v22, v26
	v_add_f32_e32 v30, v30, v31
	v_add_f32_e32 v34, v34, v35
	v_add_f32_e32 v32, v32, v33
	v_add_f32_e32 v36, v36, v37
	v_add_f32_e32 v30, v30, v32
	v_add_f32_e32 v34, v34, v36
	v_add_f32_e32 v30, v30, v34
	v_add_f32_e32 v38, v38, v39
	v_add_f32_e32 v42, v42, v43
	v_add_f32_e32 v40, v40, v41
	v_add_f32_e32 v44, v44, v45
	v_add_f32_e32 v38, v38, v40
	v_add_f32_e32 v42, v42, v44
	v_add_f32_e32 v38, v38, v42
	v_add_f32_e32 v46, v46, v47
	v_add_f32_e32 v50, v50, v51
	v_add_f32_e32 v48, v48, v49
	v_add_f32_e32 v52, v52, v53
	v_add_f32_e32 v46, v46, v48
	v_add_f32_e32 v50, v50, v52
	v_add_f32_e32 v46, v46, v50
	v_add_f32_e32 v54, v54, v55
	v_add_f32_e32 v58, v58, v59
	v_add_f32_e32 v56, v56, v57
	v_add_f32_e32 v60, v60, v61
	v_add_f32_e32 v54, v54, v56
	v_add_f32_e32 v58, v58, v60
	v_add_f32_e32 v54, v54, v58
	v_add_f32_e32 v62, v62, v63
	v_add_f32_e32 v66, v66, v67
	v_add_f32_e32 v64, v64, v65
	v_add_f32_e32 v68, v68, v69
	v_add_f32_e32 v62, v62, v64
	v_add_f32_e32 v66, v66, v68
	v_add_f32_e32 v62, v62, v66
	v_add_f32_e32 v70, v70, v71
	v_add_f32_e32 v74, v74, v75
	v_add_f32_e32 v72, v72, v73
	v_add_f32_e32 v76, v76, v77
	v_add_f32_e32 v70, v70, v72
	v_add_f32_e32 v74, v74, v76
	v_add_f32_e32 v70, v70, v74
	v_add_f32_e32 v78, v78, v79
	v_add_f32_e32 v82, v82, v83
	v_add_f32_e32 v80, v80, v81
	v_add_f32_e32 v84, v84, v85
	v_add_f32_e32 v78, v78, v80
	v_add_f32_e32 v82, v82, v84
	v_add_f32_e32 v78, v78, v82
	v_add_f32_e32 v86, v86, v87
	v_add_f32_e32 v90, v90, v91
	v_add_f32_e32 v88, v88, v89
	v_add_f32_e32 v92, v92, v93
	v_add_f32_e32 v86, v86, v88
	v_add_f32_e32 v90, v90, v92
	v_add_f32_e32 v86, v86, v90
	v_add_f32_e32 v94, v94, v95
	v_add_f32_e32 v98, v98, v99
	v_add_f32_e32 v96, v96, v97
	v_add_f32_e32 v100, v100, v101
	v_add_f32_e32 v94, v94, v96
	v_add_f32_e32 v98, v98, v100
	v_add_f32_e32 v94, v94, v98
	v_add_f32_e32 v102, v102, v103
	v_add_f32_e32 v106, v106, v107
	v_add_f32_e32 v104, v104, v105
	v_add_f32_e32 v108, v108, v109
	v_add_f32_e32 v102, v102, v104
	v_add_f32_e32 v106, v106, v108
	v_add_f32_e32 v102, v102, v106
	ds_bpermute_b32 v110, v11, v14
	ds_bpermute_b32 v111, v11, v22
	ds_bpermute_b32 v112, v11, v30
	ds_bpermute_b32 v113, v11, v38
	ds_bpermute_b32 v114, v11, v46
	ds_bpermute_b32 v115, v11, v54
	ds_bpermute_b32 v116, v11, v62
	ds_bpermute_b32 v117, v11, v70
	ds_bpermute_b32 v118, v11, v78
	ds_bpermute_b32 v119, v11, v86
	ds_bpermute_b32 v120, v11, v94
	ds_bpermute_b32 v121, v11, v102
	s_and_saveexec_b64 s[12:13], s[6:7]
	s_waitcnt lgkmcnt(0)
	v_add_f32_e32 v14, v14, v110
	v_fmamk_f32 v14, v14, 0x3a800000, v188
	v_mul_f32_e32 v15, 0x4b800000, v14
	v_cmp_gt_f32_e32 vcc, s90, v14
	s_nop 1
	v_cndmask_b32_e32 v14, v14, v15, vcc
	v_rsq_f32_e32 v14, v14
	s_nop 0
	v_mul_f32_e32 v15, 0x45800000, v14
	v_cndmask_b32_e32 v14, v14, v15, vcc
	ds_write_b32 v9, v14
	v_add_f32_e32 v22, v22, v111
	v_fmamk_f32 v22, v22, 0x3a800000, v188
	v_mul_f32_e32 v23, 0x4b800000, v22
	v_cmp_gt_f32_e32 vcc, s90, v22
	s_nop 1
	v_cndmask_b32_e32 v22, v22, v23, vcc
	v_rsq_f32_e32 v22, v22
	s_nop 0
	v_mul_f32_e32 v23, 0x45800000, v22
	v_cndmask_b32_e32 v22, v22, v23, vcc
	ds_write_b32 v9, v22 offset:1024
	v_add_f32_e32 v30, v30, v112
	v_fmamk_f32 v30, v30, 0x3a800000, v188
	v_mul_f32_e32 v31, 0x4b800000, v30
	v_cmp_gt_f32_e32 vcc, s90, v30
	s_nop 1
	v_cndmask_b32_e32 v30, v30, v31, vcc
	v_rsq_f32_e32 v30, v30
	s_nop 0
	v_mul_f32_e32 v31, 0x45800000, v30
	v_cndmask_b32_e32 v30, v30, v31, vcc
	ds_write_b32 v9, v30 offset:2048
	v_add_f32_e32 v38, v38, v113
	v_fmamk_f32 v38, v38, 0x3a800000, v188
	v_mul_f32_e32 v39, 0x4b800000, v38
	v_cmp_gt_f32_e32 vcc, s90, v38
	s_nop 1
	v_cndmask_b32_e32 v38, v38, v39, vcc
	v_rsq_f32_e32 v38, v38
	s_nop 0
	v_mul_f32_e32 v39, 0x45800000, v38
	v_cndmask_b32_e32 v38, v38, v39, vcc
	ds_write_b32 v9, v38 offset:3072
	v_add_f32_e32 v46, v46, v114
	v_fmamk_f32 v46, v46, 0x3a800000, v188
	v_mul_f32_e32 v47, 0x4b800000, v46
	v_cmp_gt_f32_e32 vcc, s90, v46
	s_nop 1
	v_cndmask_b32_e32 v46, v46, v47, vcc
	v_rsq_f32_e32 v46, v46
	s_nop 0
	v_mul_f32_e32 v47, 0x45800000, v46
	v_cndmask_b32_e32 v46, v46, v47, vcc
	ds_write_b32 v9, v46 offset:4096
	v_add_f32_e32 v54, v54, v115
	v_fmamk_f32 v54, v54, 0x3a800000, v188
	v_mul_f32_e32 v55, 0x4b800000, v54
	v_cmp_gt_f32_e32 vcc, s90, v54
	s_nop 1
	v_cndmask_b32_e32 v54, v54, v55, vcc
	v_rsq_f32_e32 v54, v54
	s_nop 0
	v_mul_f32_e32 v55, 0x45800000, v54
	v_cndmask_b32_e32 v54, v54, v55, vcc
	ds_write_b32 v9, v54 offset:5120
	v_add_f32_e32 v62, v62, v116
	v_fmamk_f32 v62, v62, 0x3a800000, v188
	v_mul_f32_e32 v63, 0x4b800000, v62
	v_cmp_gt_f32_e32 vcc, s90, v62
	s_nop 1
	v_cndmask_b32_e32 v62, v62, v63, vcc
	v_rsq_f32_e32 v62, v62
	s_nop 0
	v_mul_f32_e32 v63, 0x45800000, v62
	v_cndmask_b32_e32 v62, v62, v63, vcc
	ds_write_b32 v9, v62 offset:6144
	v_add_f32_e32 v70, v70, v117
	v_fmamk_f32 v70, v70, 0x3a800000, v188
	v_mul_f32_e32 v71, 0x4b800000, v70
	v_cmp_gt_f32_e32 vcc, s90, v70
	s_nop 1
	v_cndmask_b32_e32 v70, v70, v71, vcc
	v_rsq_f32_e32 v70, v70
	s_nop 0
	v_mul_f32_e32 v71, 0x45800000, v70
	v_cndmask_b32_e32 v70, v70, v71, vcc
	ds_write_b32 v9, v70 offset:7168
	v_add_f32_e32 v78, v78, v118
	v_fmamk_f32 v78, v78, 0x3a800000, v188
	v_mul_f32_e32 v79, 0x4b800000, v78
	v_cmp_gt_f32_e32 vcc, s90, v78
	s_nop 1
	v_cndmask_b32_e32 v78, v78, v79, vcc
	v_rsq_f32_e32 v78, v78
	s_nop 0
	v_mul_f32_e32 v79, 0x45800000, v78
	v_cndmask_b32_e32 v78, v78, v79, vcc
	ds_write_b32 v9, v78 offset:8192
	v_add_f32_e32 v86, v86, v119
	v_fmamk_f32 v86, v86, 0x3a800000, v188
	v_mul_f32_e32 v87, 0x4b800000, v86
	v_cmp_gt_f32_e32 vcc, s90, v86
	s_nop 1
	v_cndmask_b32_e32 v86, v86, v87, vcc
	v_rsq_f32_e32 v86, v86
	s_nop 0
	v_mul_f32_e32 v87, 0x45800000, v86
	v_cndmask_b32_e32 v86, v86, v87, vcc
	ds_write_b32 v9, v86 offset:9216
	v_add_f32_e32 v94, v94, v120
	v_fmamk_f32 v94, v94, 0x3a800000, v188
	v_mul_f32_e32 v95, 0x4b800000, v94
	v_cmp_gt_f32_e32 vcc, s90, v94
	s_nop 1
	v_cndmask_b32_e32 v94, v94, v95, vcc
	v_rsq_f32_e32 v94, v94
	s_nop 0
	v_mul_f32_e32 v95, 0x45800000, v94
	v_cndmask_b32_e32 v94, v94, v95, vcc
	ds_write_b32 v9, v94 offset:10240
	v_add_f32_e32 v102, v102, v121
	v_fmamk_f32 v102, v102, 0x3a800000, v188
	v_mul_f32_e32 v103, 0x4b800000, v102
	v_cmp_gt_f32_e32 vcc, s90, v102
	s_nop 1
	v_cndmask_b32_e32 v102, v102, v103, vcc
	v_rsq_f32_e32 v102, v102
	s_nop 0
	v_mul_f32_e32 v103, 0x45800000, v102
	v_cndmask_b32_e32 v102, v102, v103, vcc
	ds_write_b32 v9, v102 offset:11264
	s_or_b64 exec, exec, s[12:13]

; template <int PH, int SUB> __device__ __forceinline__ bool sched_next(unsigned char* ws, int layer, int i, Unit& u, const void* ug = nullptr) {
;     ...
;     if constexpr (PH == PH_MERGE) { const int ui = i / 3, r = i % 3, L = ui * G + c; if (L >= 512) return false; tile_map(L, 128, 4, u.pm, u.pn); u.aux = r; u.ord = ui;
; template <int PH, int SUB> __device__ __forceinline__ void rs_fill(LAS unsigned char* lds, const Epi& E) {
;     ...
;         for (int i = 0; i < 12; ++i) { Unit u; if (!sched_next<PH, SUB>(E.ws, E.layer, i, u)) break;
;             const int r = tidx >> 1, hf = tidx & 1; const size_t row = (size_t)(u.pm * 256 + r); f32x4 a, b;
;             { unsigned* pa = (unsigned*)(ssq + ((size_t)(2 * hf) * T_TOK + row) * 4); unsigned* pb = (unsigned*)(ssq + ((size_t)(2 * hf + 1) * T_TOK + row) * 4);
; #pragma unroll
;               for (int j = 0; j < 4; ++j) { a[j] = __uint_as_float(__hip_atomic_load(pa + j, __ATOMIC_RELAXED, __HIP_MEMORY_SCOPE_AGENT)); b[j] = __uint_as_float(__hip_atomic_load(pb + j, __ATOMIC_RELAXED, __HIP_MEMORY_SCOPE_AGENT)); } }
.LBB0_857:
	s_or_b64 exec, exec, s[2:3]
	v_readlane_b32 s2, v233, 5
	v_readlane_b32 s3, v233, 6
	s_waitcnt lgkmcnt(0)
	s_barrier
	s_load_dwordx4 s[8:11], s[2:3], 0xc8
	v_mov_b32_e32 v0, v186
	v_readlane_b32 s4, v231, 56
	v_and_b32_e32 v9, 1, v0
	s_waitcnt lgkmcnt(0)
	s_add_u32 s2, s10, 0xa800000
	v_ashrrev_i32_e32 v8, 1, v0
	v_lshlrev_b32_e32 v0, 16, v9
	s_addc_u32 s3, s11, 0
	v_or_b32_e32 v2, 0x8000, v0
	v_mov_b32_e32 v3, v1
	s_mov_b32 s14, 0
	v_cmp_eq_u32_e64 s[6:7], 0, v9
	v_lshl_add_u32 v9, v8, 2, s4
	s_mul_i32 s16, s56, 0
	s_add_i32 s16, s16, s72
	s_cmpk_gt_i32 s16, 0x1ff
	s_cbranch_scc1 .Lrsb_MG0_p2
	s_ashr_i32 s4, s16, 31
	s_lshr_b32 s4, s4, 29
	s_add_i32 s4, s16, s4
	s_ashr_i32 s5, s4, 3
	s_and_b32 s4, s4, -8
	s_sub_i32 s4, s16, s4
	s_lshr_b32 s12, s4, 31
	s_or_b32 s12, s12, 64
	s_mul_i32 s4, s12, s4
	s_add_i32 s4, s4, s5
	s_ashr_i32 s5, s4, 31
	s_lshr_b32 s5, s5, 27
	s_add_i32 s5, s4, s5
	s_ashr_i32 s12, s5, 5
	s_lshl_b32 s12, s12, 3
	s_sub_i32 s13, 0x80, s12
	s_min_u32 s13, s13, 8
	s_andn2_b32 s5, s5, 31
	s_sub_i32 s16, s4, s5
	s_waitcnt lgkmcnt(0)
	v_cvt_f32_ubyte0_e32 v11, s13
	v_cvt_f32_i32_e32 v10, s16
	v_rcp_iflag_f32_e32 v12, v11
	s_ashr_i32 s4, s16, 30
	s_or_b32 s17, s4, 1
	v_mul_f32_e32 v12, v10, v12
	v_trunc_f32_e32 v12, v12
	v_fma_f32 v10, -v12, v11, v10
	v_cvt_i32_f32_e32 v12, v12
	v_cmp_ge_f32_e64 s[4:5], |v10|, v11
	s_and_b64 s[4:5], s[4:5], exec
	s_cselect_b32 s4, s17, 0
	v_readfirstlane_b32 s5, v12
	s_add_i32 s4, s5, s4
	s_mul_i32 s4, s4, s13
	s_sub_i32 s4, s16, s4
	s_sext_i32_i8 s4, s4
	s_add_i32 s12, s12, s4
	v_lshl_add_u32 v10, s12, 8, v8
	v_ashrrev_i32_e32 v11, 31, v10
	v_lshl_add_u64 v[12:13], v[10:11], 0, v[0:1]
	v_lshl_add_u64 v[10:11], v[10:11], 0, v[2:3]
	v_lshl_add_u64 v[12:13], v[12:13], 4, s[2:3]
	v_lshl_add_u64 v[10:11], v[10:11], 4, s[2:3]
	global_load_dwordx4 v[14:17], v[12:13], off sc1
	global_load_dwordx4 v[18:21], v[10:11], off sc1
	s_mul_i32 s16, s56, 1
	s_add_i32 s16, s16, s72
	s_cmpk_gt_i32 s16, 0x1ff
	s_cbranch_scc1 .Lrsb_MG0_p2
	s_ashr_i32 s4, s16, 31
	s_lshr_b32 s4, s4, 29
	s_add_i32 s4, s16, s4
	s_ashr_i32 s5, s4, 3
	s_and_b32 s4, s4, -8
	s_sub_i32 s4, s16, s4
	s_lshr_b32 s12, s4, 31
	s_or_b32 s12, s12, 64
	s_mul_i32 s4, s12, s4
	s_add_i32 s4, s4, s5
	s_ashr_i32 s5, s4, 31
	s_lshr_b32 s5, s5, 27
	s_add_i32 s5, s4, s5
	s_ashr_i32 s12, s5, 5
	s_lshl_b32 s12, s12, 3
	s_sub_i32 s13, 0x80, s12
	s_min_u32 s13, s13, 8
	s_andn2_b32 s5, s5, 31
	s_sub_i32 s16, s4, s5
	s_waitcnt lgkmcnt(0)
	v_cvt_f32_ubyte0_e32 v11, s13
	v_cvt_f32_i32_e32 v10, s16
	v_rcp_iflag_f32_e32 v12, v11
	s_ashr_i32 s4, s16, 30
	s_or_b32 s17, s4, 1
	v_mul_f32_e32 v12, v10, v12
	v_trunc_f32_e32 v12, v12
	v_fma_f32 v10, -v12, v11, v10
	v_cvt_i32_f32_e32 v12, v12
	v_cmp_ge_f32_e64 s[4:5], |v10|, v11
	s_and_b64 s[4:5], s[4:5], exec
	s_cselect_b32 s4, s17, 0
	v_readfirstlane_b32 s5, v12
	s_add_i32 s4, s5, s4
	s_mul_i32 s4, s4, s13
	s_sub_i32 s4, s16, s4
	s_sext_i32_i8 s4, s4
	s_add_i32 s12, s12, s4
	v_lshl_add_u32 v10, s12, 8, v8
	v_ashrrev_i32_e32 v11, 31, v10
	v_lshl_add_u64 v[12:13], v[10:11], 0, v[0:1]
	v_lshl_add_u64 v[10:11], v[10:11], 0, v[2:3]
	v_lshl_add_u64 v[12:13], v[12:13], 4, s[2:3]
	v_lshl_add_u64 v[10:11], v[10:11], 4, s[2:3]
	global_load_dwordx4 v[22:25], v[12:13], off sc1
	global_load_dwordx4 v[26:29], v[10:11], off sc1
	s_mul_i32 s16, s56, 2
	s_add_i32 s16, s16, s72
	s_cmpk_gt_i32 s16, 0x1ff
	s_cbranch_scc1 .Lrsb_MG0_p2
	s_ashr_i32 s4, s16, 31
	s_lshr_b32 s4, s4, 29
	s_add_i32 s4, s16, s4
	s_ashr_i32 s5, s4, 3
	s_and_b32 s4, s4, -8
	s_sub_i32 s4, s16, s4
	s_lshr_b32 s12, s4, 31
	s_or_b32 s12, s12, 64
	s_mul_i32 s4, s12, s4
	s_add_i32 s4, s4, s5
	s_ashr_i32 s5, s4, 31
	s_lshr_b32 s5, s5, 27
	s_add_i32 s5, s4, s5
	s_ashr_i32 s12, s5, 5
	s_lshl_b32 s12, s12, 3
	s_sub_i32 s13, 0x80, s12
	s_min_u32 s13, s13, 8
	s_andn2_b32 s5, s5, 31
	s_sub_i32 s16, s4, s5
	s_waitcnt lgkmcnt(0)
	v_cvt_f32_ubyte0_e32 v11, s13
	v_cvt_f32_i32_e32 v10, s16
	v_rcp_iflag_f32_e32 v12, v11
	s_ashr_i32 s4, s16, 30
	s_or_b32 s17, s4, 1
	v_mul_f32_e32 v12, v10, v12
	v_trunc_f32_e32 v12, v12
	v_fma_f32 v10, -v12, v11, v10
	v_cvt_i32_f32_e32 v12, v12
	v_cmp_ge_f32_e64 s[4:5], |v10|, v11
	s_and_b64 s[4:5], s[4:5], exec
	s_cselect_b32 s4, s17, 0
	v_readfirstlane_b32 s5, v12
	s_add_i32 s4, s5, s4
	s_mul_i32 s4, s4, s13
	s_sub_i32 s4, s16, s4
	s_sext_i32_i8 s4, s4
	s_add_i32 s12, s12, s4
	v_lshl_add_u32 v10, s12, 8, v8
	v_ashrrev_i32_e32 v11, 31, v10
	v_lshl_add_u64 v[12:13], v[10:11], 0, v[0:1]
	v_lshl_add_u64 v[10:11], v[10:11], 0, v[2:3]
	v_lshl_add_u64 v[12:13], v[12:13], 4, s[2:3]
	v_lshl_add_u64 v[10:11], v[10:11], 4, s[2:3]
	global_load_dwordx4 v[30:33], v[12:13], off sc1
	global_load_dwordx4 v[34:37], v[10:11], off sc1
	s_mul_i32 s16, s56, 3
	s_add_i32 s16, s16, s72
	s_cmpk_gt_i32 s16, 0x1ff
	s_cbranch_scc1 .Lrsb_MG0_p2
	s_ashr_i32 s4, s16, 31
	s_lshr_b32 s4, s4, 29
	s_add_i32 s4, s16, s4
	s_ashr_i32 s5, s4, 3
	s_and_b32 s4, s4, -8
	s_sub_i32 s4, s16, s4
	s_lshr_b32 s12, s4, 31
	s_or_b32 s12, s12, 64
	s_mul_i32 s4, s12, s4
	s_add_i32 s4, s4, s5
	s_ashr_i32 s5, s4, 31
	s_lshr_b32 s5, s5, 27
	s_add_i32 s5, s4, s5
	s_ashr_i32 s12, s5, 5
	s_lshl_b32 s12, s12, 3
	s_sub_i32 s13, 0x80, s12
	s_min_u32 s13, s13, 8
	s_andn2_b32 s5, s5, 31
	s_sub_i32 s16, s4, s5
	s_waitcnt lgkmcnt(0)
	v_cvt_f32_ubyte0_e32 v11, s13
	v_cvt_f32_i32_e32 v10, s16
	v_rcp_iflag_f32_e32 v12, v11
	s_ashr_i32 s4, s16, 30
	s_or_b32 s17, s4, 1
	v_mul_f32_e32 v12, v10, v12
	v_trunc_f32_e32 v12, v12
	v_fma_f32 v10, -v12, v11, v10
	v_cvt_i32_f32_e32 v12, v12
	v_cmp_ge_f32_e64 s[4:5], |v10|, v11
	s_and_b64 s[4:5], s[4:5], exec
	s_cselect_b32 s4, s17, 0
	v_readfirstlane_b32 s5, v12
	s_add_i32 s4, s5, s4
	s_mul_i32 s4, s4, s13
	s_sub_i32 s4, s16, s4
	s_sext_i32_i8 s4, s4
	s_add_i32 s12, s12, s4
	v_lshl_add_u32 v10, s12, 8, v8
	v_ashrrev_i32_e32 v11, 31, v10
	v_lshl_add_u64 v[12:13], v[10:11], 0, v[0:1]
	v_lshl_add_u64 v[10:11], v[10:11], 0, v[2:3]
	v_lshl_add_u64 v[12:13], v[12:13], 4, s[2:3]
	v_lshl_add_u64 v[10:11], v[10:11], 4, s[2:3]
	global_load_dwordx4 v[38:41], v[12:13], off sc1
	global_load_dwordx4 v[42:45], v[10:11], off sc1
; template <int PH, int SUB> __device__ __forceinline__ void rs_fill(LAS unsigned char* lds, const Epi& E) {
;     ...
;             float t = ((a[0] + a[1]) + (a[2] + a[3])) + ((b[0] + b[1]) + (b[2] + b[3])); t += __shfl_xor(t, 1);
;             if (hf == 0) tab[u.ord * 256 + r] = rsqrtf(t * (1.0f / 1024.0f) + 1e-6f); }
;         __syncthreads();
.Lrsb_MG0_p2:
	v_cmp_lt_i32_e32 vcc, v191, v192
	s_nop 1
	v_cndmask_b32_e32 v11, v190, v191, vcc
	v_lshlrev_b32_e32 v11, 2, v11
	s_waitcnt vmcnt(0)
	v_add_f32_e32 v14, v14, v15
	v_add_f32_e32 v18, v18, v19
	v_add_f32_e32 v16, v16, v17
	v_add_f32_e32 v20, v20, v21
	v_add_f32_e32 v14, v14, v16
	v_add_f32_e32 v18, v18, v20
	v_add_f32_e32 v14, v14, v18
	v_add_f32_e32 v22, v22, v23
	v_add_f32_e32 v26, v26, v27
	v_add_f32_e32 v24, v24, v25
	v_add_f32_e32 v28, v28, v29
	v_add_f32_e32 v22, v22, v24
	v_add_f32_e32 v26, v26, v28
	v_add_f32_e32 v22, v22, v26
	v_add_f32_e32 v30, v30, v31
	v_add_f32_e32 v34, v34, v35
	v_add_f32_e32 v32, v32, v33
	v_add_f32_e32 v36, v36, v37
	v_add_f32_e32 v30, v30, v32
	v_add_f32_e32 v34, v34, v36
	v_add_f32_e32 v30, v30, v34
	v_add_f32_e32 v38, v38, v39
	v_add_f32_e32 v42, v42, v43
	v_add_f32_e32 v40, v40, v41
	v_add_f32_e32 v44, v44, v45
	v_add_f32_e32 v38, v38, v40
	v_add_f32_e32 v42, v42, v44
	v_add_f32_e32 v38, v38, v42
	ds_bpermute_b32 v110, v11, v14
	ds_bpermute_b32 v111, v11, v22
	ds_bpermute_b32 v112, v11, v30
	ds_bpermute_b32 v113, v11, v38
	s_and_saveexec_b64 s[12:13], s[6:7]
	s_waitcnt lgkmcnt(0)
	v_add_f32_e32 v14, v14, v110
	v_fmamk_f32 v14, v14, 0x3a800000, v188
	v_mul_f32_e32 v15, 0x4b800000, v14
	v_cmp_gt_f32_e32 vcc, s90, v14
	s_nop 1
	v_cndmask_b32_e32 v14, v14, v15, vcc
	v_rsq_f32_e32 v14, v14
	s_nop 0
	v_mul_f32_e32 v15, 0x45800000, v14
	v_cndmask_b32_e32 v14, v14, v15, vcc
	ds_write_b32 v9, v14
	v_add_f32_e32 v22, v22, v111
	v_fmamk_f32 v22, v22, 0x3a800000, v188
	v_mul_f32_e32 v23, 0x4b800000, v22
	v_cmp_gt_f32_e32 vcc, s90, v22
	s_nop 1
	v_cndmask_b32_e32 v22, v22, v23, vcc
	v_rsq_f32_e32 v22, v22
	s_nop 0
	v_mul_f32_e32 v23, 0x45800000, v22
	v_cndmask_b32_e32 v22, v22, v23, vcc
	ds_write_b32 v9, v22 offset:1024
	v_add_f32_e32 v30, v30, v112
	v_fmamk_f32 v30, v30, 0x3a800000, v188
	v_mul_f32_e32 v31, 0x4b800000, v30
	v_cmp_gt_f32_e32 vcc, s90, v30
	s_nop 1
	v_cndmask_b32_e32 v30, v30, v31, vcc
	v_rsq_f32_e32 v30, v30
	s_nop 0
	v_mul_f32_e32 v31, 0x45800000, v30
	v_cndmask_b32_e32 v30, v30, v31, vcc
	ds_write_b32 v9, v30 offset:2048
	v_add_f32_e32 v38, v38, v113
	v_fmamk_f32 v38, v38, 0x3a800000, v188
	v_mul_f32_e32 v39, 0x4b800000, v38
	v_cmp_gt_f32_e32 vcc, s90, v38
	s_nop 1
	v_cndmask_b32_e32 v38, v38, v39, vcc
	v_rsq_f32_e32 v38, v38
	s_nop 0
	v_mul_f32_e32 v39, 0x45800000, v38
	v_cndmask_b32_e32 v38, v38, v39, vcc
	ds_write_b32 v9, v38 offset:3072
	s_or_b64 exec, exec, s[12:13]

; template <int PH, int SUB> __device__ __forceinline__ void rs_fill(LAS unsigned char* lds, const Epi& E) {
;     ...
;         for (int i = 0; i < 12; ++i) { Unit u; if (!sched_next<PH, SUB>(E.ws, E.layer, i, u)) break;
;             const int r = tidx >> 1, hf = tidx & 1; const size_t row = (size_t)(u.pm * 256 + r); f32x4 a, b;
;             { unsigned* pa = (unsigned*)(ssq + ((size_t)(2 * hf) * T_TOK + row) * 4); unsigned* pb = (unsigned*)(ssq + ((size_t)(2 * hf + 1) * T_TOK + row) * 4);
; #pragma unroll
;               for (int j = 0; j < 4; ++j) { a[j] = __uint_as_float(__hip_atomic_load(pa + j, __ATOMIC_RELAXED, __HIP_MEMORY_SCOPE_AGENT)); b[j] = __uint_as_float(__hip_atomic_load(pb + j, __ATOMIC_RELAXED, __HIP_MEMORY_SCOPE_AGENT)); } }
.LBB0_1105:
	s_or_b64 exec, exec, s[2:3]
	v_readlane_b32 s2, v233, 5
	v_readlane_b32 s3, v233, 6
	s_waitcnt lgkmcnt(0)
	s_barrier
	s_load_dwordx2 s[2:3], s[2:3], 0xd0
	v_mov_b32_e32 v0, v186
	v_readlane_b32 s4, v231, 56
	v_and_b32_e32 v9, 1, v0
	s_waitcnt lgkmcnt(0)
	s_add_u32 s8, s2, 0xaa00000
	v_ashrrev_i32_e32 v8, 1, v0
	v_lshlrev_b32_e32 v0, 16, v9
	s_addc_u32 s9, s3, 0
	v_or_b32_e32 v2, 0x8000, v0
	v_mov_b32_e32 v3, v1
	v_cmp_eq_u32_e64 s[6:7], 0, v9
	v_lshl_add_u32 v9, v8, 2, s4
	s_mov_b32 s13, s72
	s_cmpk_gt_i32 s13, 0xaff
	s_cbranch_scc1 .Lrsb_FFI_p2
	s_ashr_i32 s4, s13, 31
	s_lshr_b32 s4, s4, 29
	s_add_i32 s4, s13, s4
	s_ashr_i32 s5, s4, 3
	s_and_b32 s4, s4, -8
	s_sub_i32 s4, s13, s4
	s_lshr_b32 s10, s4, 31
	s_or_b32 s10, s10, 0x160
	s_mul_i32 s4, s10, s4
	s_add_i32 s4, s4, s5
	s_mul_hi_i32 s5, s4, 0x2e8ba2e9
	s_lshr_b32 s10, s5, 31
	s_ashr_i32 s5, s5, 5
	s_add_i32 s5, s5, s10
	s_lshl_b32 s10, s5, 3
	s_sub_i32 s11, 0x80, s10
	s_min_u32 s11, s11, 8
	s_mulk_i32 s5, 0xb0
	s_sub_i32 s14, s4, s5
	s_waitcnt lgkmcnt(0)
	v_cvt_f32_ubyte0_e32 v11, s11
	v_cvt_f32_i32_e32 v10, s14
	v_rcp_iflag_f32_e32 v12, v11
	s_ashr_i32 s4, s14, 30
	s_or_b32 s15, s4, 1
	v_mul_f32_e32 v12, v10, v12
	v_trunc_f32_e32 v12, v12
	v_fma_f32 v10, -v12, v11, v10
	v_cvt_i32_f32_e32 v12, v12
	v_cmp_ge_f32_e64 s[4:5], |v10|, v11
	s_and_b64 s[4:5], s[4:5], exec
	s_cselect_b32 s4, s15, 0
	v_readfirstlane_b32 s5, v12
	s_add_i32 s4, s5, s4
	s_mul_i32 s4, s4, s11
	s_sub_i32 s4, s14, s4
	s_sext_i32_i16 s4, s4
	s_add_i32 s10, s10, s4
	v_lshl_add_u32 v10, s10, 8, v8
	v_ashrrev_i32_e32 v11, 31, v10
	v_lshl_add_u64 v[12:13], v[10:11], 0, v[0:1]
	v_lshl_add_u64 v[10:11], v[10:11], 0, v[2:3]
	v_lshl_add_u64 v[12:13], v[12:13], 4, s[8:9]
	v_lshl_add_u64 v[10:11], v[10:11], 4, s[8:9]
	global_load_dwordx4 v[14:17], v[12:13], off sc1
	global_load_dwordx4 v[18:21], v[10:11], off sc1
	s_add_i32 s13, s13, s56
	s_cmpk_gt_i32 s13, 0xaff
	s_cbranch_scc1 .Lrsb_FFI_p2
	s_ashr_i32 s4, s13, 31
	s_lshr_b32 s4, s4, 29
	s_add_i32 s4, s13, s4
	s_ashr_i32 s5, s4, 3
	s_and_b32 s4, s4, -8
	s_sub_i32 s4, s13, s4
	s_lshr_b32 s10, s4, 31
	s_or_b32 s10, s10, 0x160
	s_mul_i32 s4, s10, s4
	s_add_i32 s4, s4, s5
	s_mul_hi_i32 s5, s4, 0x2e8ba2e9
	s_lshr_b32 s10, s5, 31
	s_ashr_i32 s5, s5, 5
	s_add_i32 s5, s5, s10
	s_lshl_b32 s10, s5, 3
	s_sub_i32 s11, 0x80, s10
	s_min_u32 s11, s11, 8
	s_mulk_i32 s5, 0xb0
	s_sub_i32 s14, s4, s5
	s_waitcnt lgkmcnt(0)
	v_cvt_f32_ubyte0_e32 v11, s11
	v_cvt_f32_i32_e32 v10, s14
	v_rcp_iflag_f32_e32 v12, v11
	s_ashr_i32 s4, s14, 30
	s_or_b32 s15, s4, 1
	v_mul_f32_e32 v12, v10, v12
	v_trunc_f32_e32 v12, v12
	v_fma_f32 v10, -v12, v11, v10
	v_cvt_i32_f32_e32 v12, v12
	v_cmp_ge_f32_e64 s[4:5], |v10|, v11
	s_and_b64 s[4:5], s[4:5], exec
	s_cselect_b32 s4, s15, 0
	v_readfirstlane_b32 s5, v12
	s_add_i32 s4, s5, s4
	s_mul_i32 s4, s4, s11
	s_sub_i32 s4, s14, s4
	s_sext_i32_i16 s4, s4
	s_add_i32 s10, s10, s4
	v_lshl_add_u32 v10, s10, 8, v8
	v_ashrrev_i32_e32 v11, 31, v10
	v_lshl_add_u64 v[12:13], v[10:11], 0, v[0:1]
	v_lshl_add_u64 v[10:11], v[10:11], 0, v[2:3]
	v_lshl_add_u64 v[12:13], v[12:13], 4, s[8:9]
	v_lshl_add_u64 v[10:11], v[10:11], 4, s[8:9]
	global_load_dwordx4 v[22:25], v[12:13], off sc1
	global_load_dwordx4 v[26:29], v[10:11], off sc1
	s_add_i32 s13, s13, s56
	s_cmpk_gt_i32 s13, 0xaff
	s_cbranch_scc1 .Lrsb_FFI_p2
	s_ashr_i32 s4, s13, 31
	s_lshr_b32 s4, s4, 29
	s_add_i32 s4, s13, s4
	s_ashr_i32 s5, s4, 3
	s_and_b32 s4, s4, -8
	s_sub_i32 s4, s13, s4
	s_lshr_b32 s10, s4, 31
	s_or_b32 s10, s10, 0x160
	s_mul_i32 s4, s10, s4
	s_add_i32 s4, s4, s5
	s_mul_hi_i32 s5, s4, 0x2e8ba2e9
	s_lshr_b32 s10, s5, 31
	s_ashr_i32 s5, s5, 5
	s_add_i32 s5, s5, s10
	s_lshl_b32 s10, s5, 3
	s_sub_i32 s11, 0x80, s10
	s_min_u32 s11, s11, 8
	s_mulk_i32 s5, 0xb0
	s_sub_i32 s14, s4, s5
	s_waitcnt lgkmcnt(0)
	v_cvt_f32_ubyte0_e32 v11, s11
	v_cvt_f32_i32_e32 v10, s14
	v_rcp_iflag_f32_e32 v12, v11
	s_ashr_i32 s4, s14, 30
	s_or_b32 s15, s4, 1
	v_mul_f32_e32 v12, v10, v12
	v_trunc_f32_e32 v12, v12
	v_fma_f32 v10, -v12, v11, v10
	v_cvt_i32_f32_e32 v12, v12
	v_cmp_ge_f32_e64 s[4:5], |v10|, v11
	s_and_b64 s[4:5], s[4:5], exec
	s_cselect_b32 s4, s15, 0
	v_readfirstlane_b32 s5, v12
	s_add_i32 s4, s5, s4
	s_mul_i32 s4, s4, s11
	s_sub_i32 s4, s14, s4
	s_sext_i32_i16 s4, s4
	s_add_i32 s10, s10, s4
	v_lshl_add_u32 v10, s10, 8, v8
	v_ashrrev_i32_e32 v11, 31, v10
	v_lshl_add_u64 v[12:13], v[10:11], 0, v[0:1]
	v_lshl_add_u64 v[10:11], v[10:11], 0, v[2:3]
	v_lshl_add_u64 v[12:13], v[12:13], 4, s[8:9]
	v_lshl_add_u64 v[10:11], v[10:11], 4, s[8:9]
	global_load_dwordx4 v[30:33], v[12:13], off sc1
	global_load_dwordx4 v[34:37], v[10:11], off sc1
	s_add_i32 s13, s13, s56
	s_cmpk_gt_i32 s13, 0xaff
	s_cbranch_scc1 .Lrsb_FFI_p2
	s_ashr_i32 s4, s13, 31
	s_lshr_b32 s4, s4, 29
	s_add_i32 s4, s13, s4
	s_ashr_i32 s5, s4, 3
	s_and_b32 s4, s4, -8
	s_sub_i32 s4, s13, s4
	s_lshr_b32 s10, s4, 31
	s_or_b32 s10, s10, 0x160
	s_mul_i32 s4, s10, s4
	s_add_i32 s4, s4, s5
	s_mul_hi_i32 s5, s4, 0x2e8ba2e9
	s_lshr_b32 s10, s5, 31
	s_ashr_i32 s5, s5, 5
	s_add_i32 s5, s5, s10
	s_lshl_b32 s10, s5, 3
	s_sub_i32 s11, 0x80, s10
	s_min_u32 s11, s11, 8
	s_mulk_i32 s5, 0xb0
	s_sub_i32 s14, s4, s5
	s_waitcnt lgkmcnt(0)
	v_cvt_f32_ubyte0_e32 v11, s11
	v_cvt_f32_i32_e32 v10, s14
	v_rcp_iflag_f32_e32 v12, v11
	s_ashr_i32 s4, s14, 30
	s_or_b32 s15, s4, 1
	v_mul_f32_e32 v12, v10, v12
	v_trunc_f32_e32 v12, v12
	v_fma_f32 v10, -v12, v11, v10
	v_cvt_i32_f32_e32 v12, v12
	v_cmp_ge_f32_e64 s[4:5], |v10|, v11
	s_and_b64 s[4:5], s[4:5], exec
	s_cselect_b32 s4, s15, 0
	v_readfirstlane_b32 s5, v12
	s_add_i32 s4, s5, s4
	s_mul_i32 s4, s4, s11
	s_sub_i32 s4, s14, s4
	s_sext_i32_i16 s4, s4
	s_add_i32 s10, s10, s4
	v_lshl_add_u32 v10, s10, 8, v8
	v_ashrrev_i32_e32 v11, 31, v10
	v_lshl_add_u64 v[12:13], v[10:11], 0, v[0:1]
	v_lshl_add_u64 v[10:11], v[10:11], 0, v[2:3]
	v_lshl_add_u64 v[12:13], v[12:13], 4, s[8:9]
	v_lshl_add_u64 v[10:11], v[10:11], 4, s[8:9]
	global_load_dwordx4 v[38:41], v[12:13], off sc1
	global_load_dwordx4 v[42:45], v[10:11], off sc1
	s_add_i32 s13, s13, s56
	s_cmpk_gt_i32 s13, 0xaff
	s_cbranch_scc1 .Lrsb_FFI_p2
; template <int PH, int SUB> __device__ __forceinline__ void rs_fill(LAS unsigned char* lds, const Epi& E) {
;     ...
;         for (int i = 0; i < 12; ++i) { Unit u; if (!sched_next<PH, SUB>(E.ws, E.layer, i, u)) break;
;             const int r = tidx >> 1, hf = tidx & 1; const size_t row = (size_t)(u.pm * 256 + r); f32x4 a, b;
;             { unsigned* pa = (unsigned*)(ssq + ((size_t)(2 * hf) * T_TOK + row) * 4); unsigned* pb = (unsigned*)(ssq + ((size_t)(2 * hf + 1) * T_TOK + row) * 4);
; #pragma unroll
;               for (int j = 0; j < 4; ++j) { a[j] = __uint_as_float(__hip_atomic_load(pa + j, __ATOMIC_RELAXED, __HIP_MEMORY_SCOPE_AGENT)); b[j] = __uint_as_float(__hip_atomic_load(pb + j, __ATOMIC_RELAXED, __HIP_MEMORY_SCOPE_AGENT)); } }
	s_ashr_i32 s4, s13, 31
	s_lshr_b32 s4, s4, 29
	s_add_i32 s4, s13, s4
	s_ashr_i32 s5, s4, 3
	s_and_b32 s4, s4, -8
	s_sub_i32 s4, s13, s4
	s_lshr_b32 s10, s4, 31
	s_or_b32 s10, s10, 0x160
	s_mul_i32 s4, s10, s4
	s_add_i32 s4, s4, s5
	s_mul_hi_i32 s5, s4, 0x2e8ba2e9
	s_lshr_b32 s10, s5, 31
	s_ashr_i32 s5, s5, 5
	s_add_i32 s5, s5, s10
	s_lshl_b32 s10, s5, 3
	s_sub_i32 s11, 0x80, s10
	s_min_u32 s11, s11, 8
	s_mulk_i32 s5, 0xb0
	s_sub_i32 s14, s4, s5
	s_waitcnt lgkmcnt(0)
	v_cvt_f32_ubyte0_e32 v11, s11
	v_cvt_f32_i32_e32 v10, s14
	v_rcp_iflag_f32_e32 v12, v11
	s_ashr_i32 s4, s14, 30
	s_or_b32 s15, s4, 1
	v_mul_f32_e32 v12, v10, v12
	v_trunc_f32_e32 v12, v12
	v_fma_f32 v10, -v12, v11, v10
	v_cvt_i32_f32_e32 v12, v12
	v_cmp_ge_f32_e64 s[4:5], |v10|, v11
	s_and_b64 s[4:5], s[4:5], exec
	s_cselect_b32 s4, s15, 0
	v_readfirstlane_b32 s5, v12
	s_add_i32 s4, s5, s4
	s_mul_i32 s4, s4, s11
	s_sub_i32 s4, s14, s4
	s_sext_i32_i16 s4, s4
	s_add_i32 s10, s10, s4
	v_lshl_add_u32 v10, s10, 8, v8
	v_ashrrev_i32_e32 v11, 31, v10
	v_lshl_add_u64 v[12:13], v[10:11], 0, v[0:1]
	v_lshl_add_u64 v[10:11], v[10:11], 0, v[2:3]
	v_lshl_add_u64 v[12:13], v[12:13], 4, s[8:9]
	v_lshl_add_u64 v[10:11], v[10:11], 4, s[8:9]
	global_load_dwordx4 v[46:49], v[12:13], off sc1
	global_load_dwordx4 v[50:53], v[10:11], off sc1
	s_add_i32 s13, s13, s56
	s_cmpk_gt_i32 s13, 0xaff
	s_cbranch_scc1 .Lrsb_FFI_p2
	s_ashr_i32 s4, s13, 31
	s_lshr_b32 s4, s4, 29
	s_add_i32 s4, s13, s4
	s_ashr_i32 s5, s4, 3
	s_and_b32 s4, s4, -8
	s_sub_i32 s4, s13, s4
	s_lshr_b32 s10, s4, 31
	s_or_b32 s10, s10, 0x160
	s_mul_i32 s4, s10, s4
	s_add_i32 s4, s4, s5
	s_mul_hi_i32 s5, s4, 0x2e8ba2e9
	s_lshr_b32 s10, s5, 31
	s_ashr_i32 s5, s5, 5
	s_add_i32 s5, s5, s10
	s_lshl_b32 s10, s5, 3
	s_sub_i32 s11, 0x80, s10
	s_min_u32 s11, s11, 8
	s_mulk_i32 s5, 0xb0
	s_sub_i32 s14, s4, s5
	s_waitcnt lgkmcnt(0)
	v_cvt_f32_ubyte0_e32 v11, s11
	v_cvt_f32_i32_e32 v10, s14
	v_rcp_iflag_f32_e32 v12, v11
	s_ashr_i32 s4, s14, 30
	s_or_b32 s15, s4, 1
	v_mul_f32_e32 v12, v10, v12
	v_trunc_f32_e32 v12, v12
	v_fma_f32 v10, -v12, v11, v10
	v_cvt_i32_f32_e32 v12, v12
	v_cmp_ge_f32_e64 s[4:5], |v10|, v11
	s_and_b64 s[4:5], s[4:5], exec
	s_cselect_b32 s4, s15, 0
	v_readfirstlane_b32 s5, v12
	s_add_i32 s4, s5, s4
	s_mul_i32 s4, s4, s11
	s_sub_i32 s4, s14, s4
	s_sext_i32_i16 s4, s4
	s_add_i32 s10, s10, s4
	v_lshl_add_u32 v10, s10, 8, v8
	v_ashrrev_i32_e32 v11, 31, v10
	v_lshl_add_u64 v[12:13], v[10:11], 0, v[0:1]
	v_lshl_add_u64 v[10:11], v[10:11], 0, v[2:3]
	v_lshl_add_u64 v[12:13], v[12:13], 4, s[8:9]
	v_lshl_add_u64 v[10:11], v[10:11], 4, s[8:9]
	global_load_dwordx4 v[54:57], v[12:13], off sc1
	global_load_dwordx4 v[58:61], v[10:11], off sc1
	s_add_i32 s13, s13, s56
	s_cmpk_gt_i32 s13, 0xaff
	s_cbranch_scc1 .Lrsb_FFI_p2
	s_ashr_i32 s4, s13, 31
	s_lshr_b32 s4, s4, 29
	s_add_i32 s4, s13, s4
	s_ashr_i32 s5, s4, 3
	s_and_b32 s4, s4, -8
	s_sub_i32 s4, s13, s4
	s_lshr_b32 s10, s4, 31
	s_or_b32 s10, s10, 0x160
	s_mul_i32 s4, s10, s4
	s_add_i32 s4, s4, s5
	s_mul_hi_i32 s5, s4, 0x2e8ba2e9
	s_lshr_b32 s10, s5, 31
	s_ashr_i32 s5, s5, 5
	s_add_i32 s5, s5, s10
	s_lshl_b32 s10, s5, 3
	s_sub_i32 s11, 0x80, s10
	s_min_u32 s11, s11, 8
	s_mulk_i32 s5, 0xb0
	s_sub_i32 s14, s4, s5
	s_waitcnt lgkmcnt(0)
	v_cvt_f32_ubyte0_e32 v11, s11
	v_cvt_f32_i32_e32 v10, s14
	v_rcp_iflag_f32_e32 v12, v11
	s_ashr_i32 s4, s14, 30
	s_or_b32 s15, s4, 1
	v_mul_f32_e32 v12, v10, v12
	v_trunc_f32_e32 v12, v12
	v_fma_f32 v10, -v12, v11, v10
	v_cvt_i32_f32_e32 v12, v12
	v_cmp_ge_f32_e64 s[4:5], |v10|, v11
	s_and_b64 s[4:5], s[4:5], exec
	s_cselect_b32 s4, s15, 0
	v_readfirstlane_b32 s5, v12
	s_add_i32 s4, s5, s4
	s_mul_i32 s4, s4, s11
	s_sub_i32 s4, s14, s4
	s_sext_i32_i16 s4, s4
	s_add_i32 s10, s10, s4
	v_lshl_add_u32 v10, s10, 8, v8
	v_ashrrev_i32_e32 v11, 31, v10
	v_lshl_add_u64 v[12:13], v[10:11], 0, v[0:1]
	v_lshl_add_u64 v[10:11], v[10:11], 0, v[2:3]
	v_lshl_add_u64 v[12:13], v[12:13], 4, s[8:9]
	v_lshl_add_u64 v[10:11], v[10:11], 4, s[8:9]
	global_load_dwordx4 v[62:65], v[12:13], off sc1
	global_load_dwordx4 v[66:69], v[10:11], off sc1
	s_add_i32 s13, s13, s56
	s_cmpk_gt_i32 s13, 0xaff
	s_cbranch_scc1 .Lrsb_FFI_p2
	s_ashr_i32 s4, s13, 31
	s_lshr_b32 s4, s4, 29
	s_add_i32 s4, s13, s4
	s_ashr_i32 s5, s4, 3
	s_and_b32 s4, s4, -8
	s_sub_i32 s4, s13, s4
	s_lshr_b32 s10, s4, 31
	s_or_b32 s10, s10, 0x160
	s_mul_i32 s4, s10, s4
	s_add_i32 s4, s4, s5
	s_mul_hi_i32 s5, s4, 0x2e8ba2e9
	s_lshr_b32 s10, s5, 31
	s_ashr_i32 s5, s5, 5
	s_add_i32 s5, s5, s10
	s_lshl_b32 s10, s5, 3
	s_sub_i32 s11, 0x80, s10
	s_min_u32 s11, s11, 8
	s_mulk_i32 s5, 0xb0
	s_sub_i32 s14, s4, s5
	s_waitcnt lgkmcnt(0)
	v_cvt_f32_ubyte0_e32 v11, s11
	v_cvt_f32_i32_e32 v10, s14
	v_rcp_iflag_f32_e32 v12, v11
	s_ashr_i32 s4, s14, 30
	s_or_b32 s15, s4, 1
	v_mul_f32_e32 v12, v10, v12
	v_trunc_f32_e32 v12, v12
	v_fma_f32 v10, -v12, v11, v10
	v_cvt_i32_f32_e32 v12, v12
	v_cmp_ge_f32_e64 s[4:5], |v10|, v11
	s_and_b64 s[4:5], s[4:5], exec
	s_cselect_b32 s4, s15, 0
	v_readfirstlane_b32 s5, v12
	s_add_i32 s4, s5, s4
	s_mul_i32 s4, s4, s11
	s_sub_i32 s4, s14, s4
	s_sext_i32_i16 s4, s4
	s_add_i32 s10, s10, s4
	v_lshl_add_u32 v10, s10, 8, v8
	v_ashrrev_i32_e32 v11, 31, v10
	v_lshl_add_u64 v[12:13], v[10:11], 0, v[0:1]
	v_lshl_add_u64 v[10:11], v[10:11], 0, v[2:3]
	v_lshl_add_u64 v[12:13], v[12:13], 4, s[8:9]
	v_lshl_add_u64 v[10:11], v[10:11], 4, s[8:9]
	global_load_dwordx4 v[70:73], v[12:13], off sc1
	global_load_dwordx4 v[74:77], v[10:11], off sc1
	s_add_i32 s13, s13, s56
	s_cmpk_gt_i32 s13, 0xaff
	s_cbranch_scc1 .Lrsb_FFI_p2
; template <int PH, int SUB> __device__ __forceinline__ void rs_fill(LAS unsigned char* lds, const Epi& E) {
;     ...
;         for (int i = 0; i < 12; ++i) { Unit u; if (!sched_next<PH, SUB>(E.ws, E.layer, i, u)) break;
;             const int r = tidx >> 1, hf = tidx & 1; const size_t row = (size_t)(u.pm * 256 + r); f32x4 a, b;
;             { unsigned* pa = (unsigned*)(ssq + ((size_t)(2 * hf) * T_TOK + row) * 4); unsigned* pb = (unsigned*)(ssq + ((size_t)(2 * hf + 1) * T_TOK + row) * 4);
; #pragma unroll
;               for (int j = 0; j < 4; ++j) { a[j] = __uint_as_float(__hip_atomic_load(pa + j, __ATOMIC_RELAXED, __HIP_MEMORY_SCOPE_AGENT)); b[j] = __uint_as_float(__hip_atomic_load(pb + j, __ATOMIC_RELAXED, __HIP_MEMORY_SCOPE_AGENT)); } }
	s_ashr_i32 s4, s13, 31
	s_lshr_b32 s4, s4, 29
	s_add_i32 s4, s13, s4
	s_ashr_i32 s5, s4, 3
	s_and_b32 s4, s4, -8
	s_sub_i32 s4, s13, s4
	s_lshr_b32 s10, s4, 31
	s_or_b32 s10, s10, 0x160
	s_mul_i32 s4, s10, s4
	s_add_i32 s4, s4, s5
	s_mul_hi_i32 s5, s4, 0x2e8ba2e9
	s_lshr_b32 s10, s5, 31
	s_ashr_i32 s5, s5, 5
	s_add_i32 s5, s5, s10
	s_lshl_b32 s10, s5, 3
	s_sub_i32 s11, 0x80, s10
	s_min_u32 s11, s11, 8
	s_mulk_i32 s5, 0xb0
	s_sub_i32 s14, s4, s5
	s_waitcnt lgkmcnt(0)
	v_cvt_f32_ubyte0_e32 v11, s11
	v_cvt_f32_i32_e32 v10, s14
	v_rcp_iflag_f32_e32 v12, v11
	s_ashr_i32 s4, s14, 30
	s_or_b32 s15, s4, 1
	v_mul_f32_e32 v12, v10, v12
	v_trunc_f32_e32 v12, v12
	v_fma_f32 v10, -v12, v11, v10
	v_cvt_i32_f32_e32 v12, v12
	v_cmp_ge_f32_e64 s[4:5], |v10|, v11
	s_and_b64 s[4:5], s[4:5], exec
	s_cselect_b32 s4, s15, 0
	v_readfirstlane_b32 s5, v12
	s_add_i32 s4, s5, s4
	s_mul_i32 s4, s4, s11
	s_sub_i32 s4, s14, s4
	s_sext_i32_i16 s4, s4
	s_add_i32 s10, s10, s4
	v_lshl_add_u32 v10, s10, 8, v8
	v_ashrrev_i32_e32 v11, 31, v10
	v_lshl_add_u64 v[12:13], v[10:11], 0, v[0:1]
	v_lshl_add_u64 v[10:11], v[10:11], 0, v[2:3]
	v_lshl_add_u64 v[12:13], v[12:13], 4, s[8:9]
	v_lshl_add_u64 v[10:11], v[10:11], 4, s[8:9]
	global_load_dwordx4 v[78:81], v[12:13], off sc1
	global_load_dwordx4 v[82:85], v[10:11], off sc1
	s_add_i32 s13, s13, s56
	s_cmpk_gt_i32 s13, 0xaff
	s_cbranch_scc1 .Lrsb_FFI_p2
	s_ashr_i32 s4, s13, 31
	s_lshr_b32 s4, s4, 29
	s_add_i32 s4, s13, s4
	s_ashr_i32 s5, s4, 3
	s_and_b32 s4, s4, -8
	s_sub_i32 s4, s13, s4
	s_lshr_b32 s10, s4, 31
	s_or_b32 s10, s10, 0x160
	s_mul_i32 s4, s10, s4
	s_add_i32 s4, s4, s5
	s_mul_hi_i32 s5, s4, 0x2e8ba2e9
	s_lshr_b32 s10, s5, 31
	s_ashr_i32 s5, s5, 5
	s_add_i32 s5, s5, s10
	s_lshl_b32 s10, s5, 3
	s_sub_i32 s11, 0x80, s10
	s_min_u32 s11, s11, 8
	s_mulk_i32 s5, 0xb0
	s_sub_i32 s14, s4, s5
	s_waitcnt lgkmcnt(0)
	v_cvt_f32_ubyte0_e32 v11, s11
	v_cvt_f32_i32_e32 v10, s14
	v_rcp_iflag_f32_e32 v12, v11
	s_ashr_i32 s4, s14, 30
	s_or_b32 s15, s4, 1
	v_mul_f32_e32 v12, v10, v12
	v_trunc_f32_e32 v12, v12
	v_fma_f32 v10, -v12, v11, v10
	v_cvt_i32_f32_e32 v12, v12
	v_cmp_ge_f32_e64 s[4:5], |v10|, v11
	s_and_b64 s[4:5], s[4:5], exec
	s_cselect_b32 s4, s15, 0
	v_readfirstlane_b32 s5, v12
	s_add_i32 s4, s5, s4
	s_mul_i32 s4, s4, s11
	s_sub_i32 s4, s14, s4
	s_sext_i32_i16 s4, s4
	s_add_i32 s10, s10, s4
	v_lshl_add_u32 v10, s10, 8, v8
	v_ashrrev_i32_e32 v11, 31, v10
	v_lshl_add_u64 v[12:13], v[10:11], 0, v[0:1]
	v_lshl_add_u64 v[10:11], v[10:11], 0, v[2:3]
	v_lshl_add_u64 v[12:13], v[12:13], 4, s[8:9]
	v_lshl_add_u64 v[10:11], v[10:11], 4, s[8:9]
	global_load_dwordx4 v[86:89], v[12:13], off sc1
	global_load_dwordx4 v[90:93], v[10:11], off sc1
	s_add_i32 s13, s13, s56
	s_cmpk_gt_i32 s13, 0xaff
	s_cbranch_scc1 .Lrsb_FFI_p2
	s_ashr_i32 s4, s13, 31
	s_lshr_b32 s4, s4, 29
	s_add_i32 s4, s13, s4
	s_ashr_i32 s5, s4, 3
	s_and_b32 s4, s4, -8
	s_sub_i32 s4, s13, s4
	s_lshr_b32 s10, s4, 31
	s_or_b32 s10, s10, 0x160
	s_mul_i32 s4, s10, s4
	s_add_i32 s4, s4, s5
	s_mul_hi_i32 s5, s4, 0x2e8ba2e9
	s_lshr_b32 s10, s5, 31
	s_ashr_i32 s5, s5, 5
	s_add_i32 s5, s5, s10
	s_lshl_b32 s10, s5, 3
	s_sub_i32 s11, 0x80, s10
	s_min_u32 s11, s11, 8
	s_mulk_i32 s5, 0xb0
	s_sub_i32 s14, s4, s5
	s_waitcnt lgkmcnt(0)
	v_cvt_f32_ubyte0_e32 v11, s11
	v_cvt_f32_i32_e32 v10, s14
	v_rcp_iflag_f32_e32 v12, v11
	s_ashr_i32 s4, s14, 30
	s_or_b32 s15, s4, 1
	v_mul_f32_e32 v12, v10, v12
	v_trunc_f32_e32 v12, v12
	v_fma_f32 v10, -v12, v11, v10
	v_cvt_i32_f32_e32 v12, v12
	v_cmp_ge_f32_e64 s[4:5], |v10|, v11
	s_and_b64 s[4:5], s[4:5], exec
	s_cselect_b32 s4, s15, 0
	v_readfirstlane_b32 s5, v12
	s_add_i32 s4, s5, s4
	s_mul_i32 s4, s4, s11
	s_sub_i32 s4, s14, s4
	s_sext_i32_i16 s4, s4
	s_add_i32 s10, s10, s4
	v_lshl_add_u32 v10, s10, 8, v8
	v_ashrrev_i32_e32 v11, 31, v10
	v_lshl_add_u64 v[12:13], v[10:11], 0, v[0:1]
	v_lshl_add_u64 v[10:11], v[10:11], 0, v[2:3]
	v_lshl_add_u64 v[12:13], v[12:13], 4, s[8:9]
	v_lshl_add_u64 v[10:11], v[10:11], 4, s[8:9]
	global_load_dwordx4 v[94:97], v[12:13], off sc1
	global_load_dwordx4 v[98:101], v[10:11], off sc1
	s_add_i32 s13, s13, s56
	s_cmpk_gt_i32 s13, 0xaff
	s_cbranch_scc1 .Lrsb_FFI_p2
	s_ashr_i32 s4, s13, 31
	s_lshr_b32 s4, s4, 29
	s_add_i32 s4, s13, s4
	s_ashr_i32 s5, s4, 3
	s_and_b32 s4, s4, -8
	s_sub_i32 s4, s13, s4
	s_lshr_b32 s10, s4, 31
	s_or_b32 s10, s10, 0x160
	s_mul_i32 s4, s10, s4
	s_add_i32 s4, s4, s5
	s_mul_hi_i32 s5, s4, 0x2e8ba2e9
	s_lshr_b32 s10, s5, 31
	s_ashr_i32 s5, s5, 5
	s_add_i32 s5, s5, s10
	s_lshl_b32 s10, s5, 3
	s_sub_i32 s11, 0x80, s10
	s_min_u32 s11, s11, 8
	s_mulk_i32 s5, 0xb0
	s_sub_i32 s14, s4, s5
	s_waitcnt lgkmcnt(0)
	v_cvt_f32_ubyte0_e32 v11, s11
	v_cvt_f32_i32_e32 v10, s14
	v_rcp_iflag_f32_e32 v12, v11
	s_ashr_i32 s4, s14, 30
	s_or_b32 s15, s4, 1
	v_mul_f32_e32 v12, v10, v12
	v_trunc_f32_e32 v12, v12
	v_fma_f32 v10, -v12, v11, v10
	v_cvt_i32_f32_e32 v12, v12
	v_cmp_ge_f32_e64 s[4:5], |v10|, v11
	s_and_b64 s[4:5], s[4:5], exec
	s_cselect_b32 s4, s15, 0
	v_readfirstlane_b32 s5, v12
	s_add_i32 s4, s5, s4
	s_mul_i32 s4, s4, s11
	s_sub_i32 s4, s14, s4
	s_sext_i32_i16 s4, s4
	s_add_i32 s10, s10, s4
	v_lshl_add_u32 v10, s10, 8, v8
	v_ashrrev_i32_e32 v11, 31, v10
	v_lshl_add_u64 v[12:13], v[10:11], 0, v[0:1]
	v_lshl_add_u64 v[10:11], v[10:11], 0, v[2:3]
	v_lshl_add_u64 v[12:13], v[12:13], 4, s[8:9]
	v_lshl_add_u64 v[10:11], v[10:11], 4, s[8:9]
	global_load_dwordx4 v[102:105], v[12:13], off sc1
	global_load_dwordx4 v[106:109], v[10:11], off sc1
	s_add_i32 s13, s13, s56
; template <int PH, int SUB> __device__ __forceinline__ void rs_fill(LAS unsigned char* lds, const Epi& E) {
;     ...
;             float t = ((a[0] + a[1]) + (a[2] + a[3])) + ((b[0] + b[1]) + (b[2] + b[3])); t += __shfl_xor(t, 1);
;             if (hf == 0) tab[u.ord * 256 + r] = rsqrtf(t * (1.0f / 1024.0f) + 1e-6f); }
.Lrsb_FFI_p2:
	v_cmp_lt_i32_e32 vcc, v191, v192
	s_nop 1
	v_cndmask_b32_e32 v11, v190, v191, vcc
	v_lshlrev_b32_e32 v11, 2, v11
	s_waitcnt vmcnt(0)
	v_add_f32_e32 v14, v14, v15
	v_add_f32_e32 v18, v18, v19
	v_add_f32_e32 v16, v16, v17
	v_add_f32_e32 v20, v20, v21
	v_add_f32_e32 v14, v14, v16
	v_add_f32_e32 v18, v18, v20
	v_add_f32_e32 v14, v14, v18
	v_add_f32_e32 v22, v22, v23
	v_add_f32_e32 v26, v26, v27
	v_add_f32_e32 v24, v24, v25
	v_add_f32_e32 v28, v28, v29
	v_add_f32_e32 v22, v22, v24
	v_add_f32_e32 v26, v26, v28
	v_add_f32_e32 v22, v22, v26
	v_add_f32_e32 v30, v30, v31
	v_add_f32_e32 v34, v34, v35
	v_add_f32_e32 v32, v32, v33
	v_add_f32_e32 v36, v36, v37
	v_add_f32_e32 v30, v30, v32
	v_add_f32_e32 v34, v34, v36
	v_add_f32_e32 v30, v30, v34
	v_add_f32_e32 v38, v38, v39
	v_add_f32_e32 v42, v42, v43
	v_add_f32_e32 v40, v40, v41
	v_add_f32_e32 v44, v44, v45
	v_add_f32_e32 v38, v38, v40
	v_add_f32_e32 v42, v42, v44
	v_add_f32_e32 v38, v38, v42
	v_add_f32_e32 v46, v46, v47
	v_add_f32_e32 v50, v50, v51
	v_add_f32_e32 v48, v48, v49
	v_add_f32_e32 v52, v52, v53
	v_add_f32_e32 v46, v46, v48
	v_add_f32_e32 v50, v50, v52
	v_add_f32_e32 v46, v46, v50
	v_add_f32_e32 v54, v54, v55
	v_add_f32_e32 v58, v58, v59
	v_add_f32_e32 v56, v56, v57
	v_add_f32_e32 v60, v60, v61
	v_add_f32_e32 v54, v54, v56
	v_add_f32_e32 v58, v58, v60
	v_add_f32_e32 v54, v54, v58
	v_add_f32_e32 v62, v62, v63
	v_add_f32_e32 v66, v66, v67
	v_add_f32_e32 v64, v64, v65
	v_add_f32_e32 v68, v68, v69
	v_add_f32_e32 v62, v62, v64
	v_add_f32_e32 v66, v66, v68
	v_add_f32_e32 v62, v62, v66
	v_add_f32_e32 v70, v70, v71
	v_add_f32_e32 v74, v74, v75
	v_add_f32_e32 v72, v72, v73
	v_add_f32_e32 v76, v76, v77
	v_add_f32_e32 v70, v70, v72
	v_add_f32_e32 v74, v74, v76
	v_add_f32_e32 v70, v70, v74
	v_add_f32_e32 v78, v78, v79
	v_add_f32_e32 v82, v82, v83
	v_add_f32_e32 v80, v80, v81
	v_add_f32_e32 v84, v84, v85
	v_add_f32_e32 v78, v78, v80
	v_add_f32_e32 v82, v82, v84
	v_add_f32_e32 v78, v78, v82
	v_add_f32_e32 v86, v86, v87
	v_add_f32_e32 v90, v90, v91
	v_add_f32_e32 v88, v88, v89
	v_add_f32_e32 v92, v92, v93
	v_add_f32_e32 v86, v86, v88
	v_add_f32_e32 v90, v90, v92
	v_add_f32_e32 v86, v86, v90
	v_add_f32_e32 v94, v94, v95
	v_add_f32_e32 v98, v98, v99
	v_add_f32_e32 v96, v96, v97
	v_add_f32_e32 v100, v100, v101
	v_add_f32_e32 v94, v94, v96
	v_add_f32_e32 v98, v98, v100
	v_add_f32_e32 v94, v94, v98
	v_add_f32_e32 v102, v102, v103
	v_add_f32_e32 v106, v106, v107
	v_add_f32_e32 v104, v104, v105
	v_add_f32_e32 v108, v108, v109
	v_add_f32_e32 v102, v102, v104
	v_add_f32_e32 v106, v106, v108
	v_add_f32_e32 v102, v102, v106
	ds_bpermute_b32 v110, v11, v14
	ds_bpermute_b32 v111, v11, v22
	ds_bpermute_b32 v112, v11, v30
	ds_bpermute_b32 v113, v11, v38
	ds_bpermute_b32 v114, v11, v46
	ds_bpermute_b32 v115, v11, v54
	ds_bpermute_b32 v116, v11, v62
	ds_bpermute_b32 v117, v11, v70
	ds_bpermute_b32 v118, v11, v78
	ds_bpermute_b32 v119, v11, v86
	ds_bpermute_b32 v120, v11, v94
	ds_bpermute_b32 v121, v11, v102
	s_and_saveexec_b64 s[10:11], s[6:7]
	s_waitcnt lgkmcnt(0)
	v_add_f32_e32 v14, v14, v110
	v_fmamk_f32 v14, v14, 0x3a800000, v188
	v_mul_f32_e32 v15, 0x4b800000, v14
	v_cmp_gt_f32_e32 vcc, s90, v14
	s_nop 1
	v_cndmask_b32_e32 v14, v14, v15, vcc
	v_rsq_f32_e32 v14, v14
	s_nop 0
	v_mul_f32_e32 v15, 0x45800000, v14
	v_cndmask_b32_e32 v14, v14, v15, vcc
	ds_write_b32 v9, v14
	v_add_f32_e32 v22, v22, v111
	v_fmamk_f32 v22, v22, 0x3a800000, v188
	v_mul_f32_e32 v23, 0x4b800000, v22
	v_cmp_gt_f32_e32 vcc, s90, v22
	s_nop 1
	v_cndmask_b32_e32 v22, v22, v23, vcc
	v_rsq_f32_e32 v22, v22
	s_nop 0
	v_mul_f32_e32 v23, 0x45800000, v22
	v_cndmask_b32_e32 v22, v22, v23, vcc
	ds_write_b32 v9, v22 offset:1024
	v_add_f32_e32 v30, v30, v112
	v_fmamk_f32 v30, v30, 0x3a800000, v188
	v_mul_f32_e32 v31, 0x4b800000, v30
	v_cmp_gt_f32_e32 vcc, s90, v30
	s_nop 1
	v_cndmask_b32_e32 v30, v30, v31, vcc
	v_rsq_f32_e32 v30, v30
	s_nop 0
	v_mul_f32_e32 v31, 0x45800000, v30
	v_cndmask_b32_e32 v30, v30, v31, vcc
	ds_write_b32 v9, v30 offset:2048
	v_add_f32_e32 v38, v38, v113
	v_fmamk_f32 v38, v38, 0x3a800000, v188
	v_mul_f32_e32 v39, 0x4b800000, v38
	v_cmp_gt_f32_e32 vcc, s90, v38
	s_nop 1
	v_cndmask_b32_e32 v38, v38, v39, vcc
	v_rsq_f32_e32 v38, v38
	s_nop 0
	v_mul_f32_e32 v39, 0x45800000, v38
	v_cndmask_b32_e32 v38, v38, v39, vcc
	ds_write_b32 v9, v38 offset:3072
	v_add_f32_e32 v46, v46, v114
	v_fmamk_f32 v46, v46, 0x3a800000, v188
	v_mul_f32_e32 v47, 0x4b800000, v46
	v_cmp_gt_f32_e32 vcc, s90, v46
	s_nop 1
	v_cndmask_b32_e32 v46, v46, v47, vcc
	v_rsq_f32_e32 v46, v46
	s_nop 0
	v_mul_f32_e32 v47, 0x45800000, v46
	v_cndmask_b32_e32 v46, v46, v47, vcc
	ds_write_b32 v9, v46 offset:4096
	v_add_f32_e32 v54, v54, v115
	v_fmamk_f32 v54, v54, 0x3a800000, v188
	v_mul_f32_e32 v55, 0x4b800000, v54
	v_cmp_gt_f32_e32 vcc, s90, v54
	s_nop 1
	v_cndmask_b32_e32 v54, v54, v55, vcc
	v_rsq_f32_e32 v54, v54
	s_nop 0
	v_mul_f32_e32 v55, 0x45800000, v54
	v_cndmask_b32_e32 v54, v54, v55, vcc
	ds_write_b32 v9, v54 offset:5120
	v_add_f32_e32 v62, v62, v116
	v_fmamk_f32 v62, v62, 0x3a800000, v188
	v_mul_f32_e32 v63, 0x4b800000, v62
	v_cmp_gt_f32_e32 vcc, s90, v62
	s_nop 1
	v_cndmask_b32_e32 v62, v62, v63, vcc
	v_rsq_f32_e32 v62, v62
	s_nop 0
	v_mul_f32_e32 v63, 0x45800000, v62
	v_cndmask_b32_e32 v62, v62, v63, vcc
	ds_write_b32 v9, v62 offset:6144
	v_add_f32_e32 v70, v70, v117
	v_fmamk_f32 v70, v70, 0x3a800000, v188
	v_mul_f32_e32 v71, 0x4b800000, v70
	v_cmp_gt_f32_e32 vcc, s90, v70
	s_nop 1
	v_cndmask_b32_e32 v70, v70, v71, vcc
	v_rsq_f32_e32 v70, v70
	s_nop 0
	v_mul_f32_e32 v71, 0x45800000, v70
	v_cndmask_b32_e32 v70, v70, v71, vcc
	ds_write_b32 v9, v70 offset:7168
	v_add_f32_e32 v78, v78, v118
	v_fmamk_f32 v78, v78, 0x3a800000, v188
	v_mul_f32_e32 v79, 0x4b800000, v78
	v_cmp_gt_f32_e32 vcc, s90, v78
	s_nop 1
	v_cndmask_b32_e32 v78, v78, v79, vcc
	v_rsq_f32_e32 v78, v78
	s_nop 0
	v_mul_f32_e32 v79, 0x45800000, v78
	v_cndmask_b32_e32 v78, v78, v79, vcc
	ds_write_b32 v9, v78 offset:8192
	v_add_f32_e32 v86, v86, v119
	v_fmamk_f32 v86, v86, 0x3a800000, v188
	v_mul_f32_e32 v87, 0x4b800000, v86
	v_cmp_gt_f32_e32 vcc, s90, v86
	s_nop 1
	v_cndmask_b32_e32 v86, v86, v87, vcc
	v_rsq_f32_e32 v86, v86
	s_nop 0
	v_mul_f32_e32 v87, 0x45800000, v86
	v_cndmask_b32_e32 v86, v86, v87, vcc
	ds_write_b32 v9, v86 offset:9216
	v_add_f32_e32 v94, v94, v120
	v_fmamk_f32 v94, v94, 0x3a800000, v188
	v_mul_f32_e32 v95, 0x4b800000, v94
	v_cmp_gt_f32_e32 vcc, s90, v94
	s_nop 1
	v_cndmask_b32_e32 v94, v94, v95, vcc
	v_rsq_f32_e32 v94, v94
	s_nop 0
	v_mul_f32_e32 v95, 0x45800000, v94
	v_cndmask_b32_e32 v94, v94, v95, vcc
	ds_write_b32 v9, v94 offset:10240
	v_add_f32_e32 v102, v102, v121
	v_fmamk_f32 v102, v102, 0x3a800000, v188
	v_mul_f32_e32 v103, 0x4b800000, v102
	v_cmp_gt_f32_e32 vcc, s90, v102
	s_nop 1
	v_cndmask_b32_e32 v102, v102, v103, vcc
	v_rsq_f32_e32 v102, v102
	s_nop 0
	v_mul_f32_e32 v103, 0x45800000, v102
	v_cndmask_b32_e32 v102, v102, v103, vcc
	ds_write_b32 v9, v102 offset:11264
	s_or_b64 exec, exec, s[10:11]

; template <int PH, int SUB> __device__ __forceinline__ void rs_fill(LAS unsigned char* lds, const Epi& E) {
;     ...
;         for (int i = 0; i < 12; ++i) { Unit u; if (!sched_next<PH, SUB>(E.ws, E.layer, i, u)) break;
;             const int r = tidx >> 1, hf = tidx & 1; const size_t row = (size_t)(u.pm * 256 + r); f32x4 a, b;
;             { unsigned* pa = (unsigned*)(ssq + ((size_t)(2 * hf) * T_TOK + row) * 4); unsigned* pb = (unsigned*)(ssq + ((size_t)(2 * hf + 1) * T_TOK + row) * 4);
; #pragma unroll
;               for (int j = 0; j < 4; ++j) { a[j] = __uint_as_float(__hip_atomic_load(pa + j, __ATOMIC_RELAXED, __HIP_MEMORY_SCOPE_AGENT)); b[j] = __uint_as_float(__hip_atomic_load(pb + j, __ATOMIC_RELAXED, __HIP_MEMORY_SCOPE_AGENT)); } }
.LBB0_1265:
	v_readlane_b32 s2, v233, 5
	v_readlane_b32 s3, v233, 6
	s_load_dwordx2 s[2:3], s[2:3], 0xd0
	v_mov_b32_e32 v0, v186
	v_readlane_b32 s4, v231, 56
	v_and_b32_e32 v9, 1, v0
	v_ashrrev_i32_e32 v8, 1, v0
	s_waitcnt lgkmcnt(0)
	s_add_u32 s8, s2, 0xac00000
	v_lshlrev_b32_e32 v0, 16, v9
	s_addc_u32 s9, s3, 0
	v_or_b32_e32 v2, 0x8000, v0
	v_mov_b32_e32 v3, v1
	v_cmp_eq_u32_e64 s[6:7], 0, v9
	v_lshl_add_u32 v9, v8, 2, s4
	s_mov_b32 s13, s72
	s_cmpk_gt_i32 s13, 0x1ff
	s_cbranch_scc1 .Lrsb_PLE1_p2
	s_ashr_i32 s4, s13, 31
	s_lshr_b32 s4, s4, 29
	s_add_i32 s4, s13, s4
	s_ashr_i32 s5, s4, 3
	s_and_b32 s4, s4, -8
	s_sub_i32 s4, s13, s4
	s_lshr_b32 s10, s4, 31
	s_or_b32 s10, s10, 64
	s_mul_i32 s4, s10, s4
	s_add_i32 s4, s4, s5
	s_ashr_i32 s5, s4, 31
	s_lshr_b32 s5, s5, 27
	s_add_i32 s5, s4, s5
	s_ashr_i32 s10, s5, 5
	s_lshl_b32 s10, s10, 3
	s_sub_i32 s11, 0x80, s10
	s_min_u32 s11, s11, 8
	s_andn2_b32 s5, s5, 31
	s_sub_i32 s14, s4, s5
	s_waitcnt lgkmcnt(0)
	v_cvt_f32_ubyte0_e32 v11, s11
	v_cvt_f32_i32_e32 v10, s14
	v_rcp_iflag_f32_e32 v12, v11
	s_ashr_i32 s4, s14, 30
	s_or_b32 s15, s4, 1
	v_mul_f32_e32 v12, v10, v12
	v_trunc_f32_e32 v12, v12
	v_fma_f32 v10, -v12, v11, v10
	v_cvt_i32_f32_e32 v12, v12
	v_cmp_ge_f32_e64 s[4:5], |v10|, v11
	s_and_b64 s[4:5], s[4:5], exec
	s_cselect_b32 s4, s15, 0
	v_readfirstlane_b32 s5, v12
	s_add_i32 s4, s5, s4
	s_mul_i32 s4, s4, s11
	s_sub_i32 s4, s14, s4
	s_sext_i32_i8 s4, s4
	s_add_i32 s10, s10, s4
	v_lshl_add_u32 v10, s10, 8, v8
	v_ashrrev_i32_e32 v11, 31, v10
	v_lshl_add_u64 v[12:13], v[10:11], 0, v[0:1]
	v_lshl_add_u64 v[10:11], v[10:11], 0, v[2:3]
	v_lshl_add_u64 v[12:13], v[12:13], 4, s[8:9]
	v_lshl_add_u64 v[10:11], v[10:11], 4, s[8:9]
	global_load_dwordx4 v[14:17], v[12:13], off sc1
	global_load_dwordx4 v[18:21], v[10:11], off sc1
	s_add_i32 s13, s13, s56
	s_cmpk_gt_i32 s13, 0x1ff
	s_cbranch_scc1 .Lrsb_PLE1_p2
	s_ashr_i32 s4, s13, 31
	s_lshr_b32 s4, s4, 29
	s_add_i32 s4, s13, s4
	s_ashr_i32 s5, s4, 3
	s_and_b32 s4, s4, -8
	s_sub_i32 s4, s13, s4
	s_lshr_b32 s10, s4, 31
	s_or_b32 s10, s10, 64
	s_mul_i32 s4, s10, s4
	s_add_i32 s4, s4, s5
	s_ashr_i32 s5, s4, 31
	s_lshr_b32 s5, s5, 27
	s_add_i32 s5, s4, s5
	s_ashr_i32 s10, s5, 5
	s_lshl_b32 s10, s10, 3
	s_sub_i32 s11, 0x80, s10
	s_min_u32 s11, s11, 8
	s_andn2_b32 s5, s5, 31
	s_sub_i32 s14, s4, s5
	s_waitcnt lgkmcnt(0)
	v_cvt_f32_ubyte0_e32 v11, s11
	v_cvt_f32_i32_e32 v10, s14
	v_rcp_iflag_f32_e32 v12, v11
	s_ashr_i32 s4, s14, 30
	s_or_b32 s15, s4, 1
	v_mul_f32_e32 v12, v10, v12
	v_trunc_f32_e32 v12, v12
	v_fma_f32 v10, -v12, v11, v10
	v_cvt_i32_f32_e32 v12, v12
	v_cmp_ge_f32_e64 s[4:5], |v10|, v11
	s_and_b64 s[4:5], s[4:5], exec
	s_cselect_b32 s4, s15, 0
	v_readfirstlane_b32 s5, v12
	s_add_i32 s4, s5, s4
	s_mul_i32 s4, s4, s11
	s_sub_i32 s4, s14, s4
	s_sext_i32_i8 s4, s4
	s_add_i32 s10, s10, s4
	v_lshl_add_u32 v10, s10, 8, v8
	v_ashrrev_i32_e32 v11, 31, v10
	v_lshl_add_u64 v[12:13], v[10:11], 0, v[0:1]
	v_lshl_add_u64 v[10:11], v[10:11], 0, v[2:3]
	v_lshl_add_u64 v[12:13], v[12:13], 4, s[8:9]
	v_lshl_add_u64 v[10:11], v[10:11], 4, s[8:9]
	global_load_dwordx4 v[22:25], v[12:13], off sc1
	global_load_dwordx4 v[26:29], v[10:11], off sc1
	s_add_i32 s13, s13, s56
	s_cmpk_gt_i32 s13, 0x1ff
	s_cbranch_scc1 .Lrsb_PLE1_p2
	s_ashr_i32 s4, s13, 31
	s_lshr_b32 s4, s4, 29
	s_add_i32 s4, s13, s4
	s_ashr_i32 s5, s4, 3
	s_and_b32 s4, s4, -8
	s_sub_i32 s4, s13, s4
	s_lshr_b32 s10, s4, 31
	s_or_b32 s10, s10, 64
	s_mul_i32 s4, s10, s4
	s_add_i32 s4, s4, s5
	s_ashr_i32 s5, s4, 31
	s_lshr_b32 s5, s5, 27
	s_add_i32 s5, s4, s5
	s_ashr_i32 s10, s5, 5
	s_lshl_b32 s10, s10, 3
	s_sub_i32 s11, 0x80, s10
	s_min_u32 s11, s11, 8
	s_andn2_b32 s5, s5, 31
	s_sub_i32 s14, s4, s5
	s_waitcnt lgkmcnt(0)
	v_cvt_f32_ubyte0_e32 v11, s11
	v_cvt_f32_i32_e32 v10, s14
	v_rcp_iflag_f32_e32 v12, v11
	s_ashr_i32 s4, s14, 30
	s_or_b32 s15, s4, 1
	v_mul_f32_e32 v12, v10, v12
	v_trunc_f32_e32 v12, v12
	v_fma_f32 v10, -v12, v11, v10
	v_cvt_i32_f32_e32 v12, v12
	v_cmp_ge_f32_e64 s[4:5], |v10|, v11
	s_and_b64 s[4:5], s[4:5], exec
	s_cselect_b32 s4, s15, 0
	v_readfirstlane_b32 s5, v12
	s_add_i32 s4, s5, s4
	s_mul_i32 s4, s4, s11
	s_sub_i32 s4, s14, s4
	s_sext_i32_i8 s4, s4
	s_add_i32 s10, s10, s4
	v_lshl_add_u32 v10, s10, 8, v8
	v_ashrrev_i32_e32 v11, 31, v10
	v_lshl_add_u64 v[12:13], v[10:11], 0, v[0:1]
	v_lshl_add_u64 v[10:11], v[10:11], 0, v[2:3]
	v_lshl_add_u64 v[12:13], v[12:13], 4, s[8:9]
	v_lshl_add_u64 v[10:11], v[10:11], 4, s[8:9]
	global_load_dwordx4 v[30:33], v[12:13], off sc1
	global_load_dwordx4 v[34:37], v[10:11], off sc1
	s_add_i32 s13, s13, s56
	s_cmpk_gt_i32 s13, 0x1ff
	s_cbranch_scc1 .Lrsb_PLE1_p2
	s_ashr_i32 s4, s13, 31
	s_lshr_b32 s4, s4, 29
	s_add_i32 s4, s13, s4
	s_ashr_i32 s5, s4, 3
	s_and_b32 s4, s4, -8
	s_sub_i32 s4, s13, s4
	s_lshr_b32 s10, s4, 31
	s_or_b32 s10, s10, 64
	s_mul_i32 s4, s10, s4
	s_add_i32 s4, s4, s5
	s_ashr_i32 s5, s4, 31
	s_lshr_b32 s5, s5, 27
	s_add_i32 s5, s4, s5
	s_ashr_i32 s10, s5, 5
	s_lshl_b32 s10, s10, 3
	s_sub_i32 s11, 0x80, s10
	s_min_u32 s11, s11, 8
	s_andn2_b32 s5, s5, 31
	s_sub_i32 s14, s4, s5
	s_waitcnt lgkmcnt(0)
	v_cvt_f32_ubyte0_e32 v11, s11
	v_cvt_f32_i32_e32 v10, s14
	v_rcp_iflag_f32_e32 v12, v11
	s_ashr_i32 s4, s14, 30
	s_or_b32 s15, s4, 1
	v_mul_f32_e32 v12, v10, v12
	v_trunc_f32_e32 v12, v12
	v_fma_f32 v10, -v12, v11, v10
	v_cvt_i32_f32_e32 v12, v12
	v_cmp_ge_f32_e64 s[4:5], |v10|, v11
	s_and_b64 s[4:5], s[4:5], exec
	s_cselect_b32 s4, s15, 0
	v_readfirstlane_b32 s5, v12
	s_add_i32 s4, s5, s4
	s_mul_i32 s4, s4, s11
	s_sub_i32 s4, s14, s4
	s_sext_i32_i8 s4, s4
	s_add_i32 s10, s10, s4
	v_lshl_add_u32 v10, s10, 8, v8
	v_ashrrev_i32_e32 v11, 31, v10
	v_lshl_add_u64 v[12:13], v[10:11], 0, v[0:1]
	v_lshl_add_u64 v[10:11], v[10:11], 0, v[2:3]
	v_lshl_add_u64 v[12:13], v[12:13], 4, s[8:9]
	v_lshl_add_u64 v[10:11], v[10:11], 4, s[8:9]
	global_load_dwordx4 v[38:41], v[12:13], off sc1
	global_load_dwordx4 v[42:45], v[10:11], off sc1
	s_add_i32 s13, s13, s56
	s_cmpk_gt_i32 s13, 0x1ff
	s_cbranch_scc1 .Lrsb_PLE1_p2
; template <int PH, int SUB> __device__ __forceinline__ void rs_fill(LAS unsigned char* lds, const Epi& E) {
;     ...
;         for (int i = 0; i < 12; ++i) { Unit u; if (!sched_next<PH, SUB>(E.ws, E.layer, i, u)) break;
;             const int r = tidx >> 1, hf = tidx & 1; const size_t row = (size_t)(u.pm * 256 + r); f32x4 a, b;
;             { unsigned* pa = (unsigned*)(ssq + ((size_t)(2 * hf) * T_TOK + row) * 4); unsigned* pb = (unsigned*)(ssq + ((size_t)(2 * hf + 1) * T_TOK + row) * 4);
; #pragma unroll
;               for (int j = 0; j < 4; ++j) { a[j] = __uint_as_float(__hip_atomic_load(pa + j, __ATOMIC_RELAXED, __HIP_MEMORY_SCOPE_AGENT)); b[j] = __uint_as_float(__hip_atomic_load(pb + j, __ATOMIC_RELAXED, __HIP_MEMORY_SCOPE_AGENT)); } }
	s_ashr_i32 s4, s13, 31
	s_lshr_b32 s4, s4, 29
	s_add_i32 s4, s13, s4
	s_ashr_i32 s5, s4, 3
	s_and_b32 s4, s4, -8
	s_sub_i32 s4, s13, s4
	s_lshr_b32 s10, s4, 31
	s_or_b32 s10, s10, 64
	s_mul_i32 s4, s10, s4
	s_add_i32 s4, s4, s5
	s_ashr_i32 s5, s4, 31
	s_lshr_b32 s5, s5, 27
	s_add_i32 s5, s4, s5
	s_ashr_i32 s10, s5, 5
	s_lshl_b32 s10, s10, 3
	s_sub_i32 s11, 0x80, s10
	s_min_u32 s11, s11, 8
	s_andn2_b32 s5, s5, 31
	s_sub_i32 s14, s4, s5
	s_waitcnt lgkmcnt(0)
	v_cvt_f32_ubyte0_e32 v11, s11
	v_cvt_f32_i32_e32 v10, s14
	v_rcp_iflag_f32_e32 v12, v11
	s_ashr_i32 s4, s14, 30
	s_or_b32 s15, s4, 1
	v_mul_f32_e32 v12, v10, v12
	v_trunc_f32_e32 v12, v12
	v_fma_f32 v10, -v12, v11, v10
	v_cvt_i32_f32_e32 v12, v12
	v_cmp_ge_f32_e64 s[4:5], |v10|, v11
	s_and_b64 s[4:5], s[4:5], exec
	s_cselect_b32 s4, s15, 0
	v_readfirstlane_b32 s5, v12
	s_add_i32 s4, s5, s4
	s_mul_i32 s4, s4, s11
	s_sub_i32 s4, s14, s4
	s_sext_i32_i8 s4, s4
	s_add_i32 s10, s10, s4
	v_lshl_add_u32 v10, s10, 8, v8
	v_ashrrev_i32_e32 v11, 31, v10
	v_lshl_add_u64 v[12:13], v[10:11], 0, v[0:1]
	v_lshl_add_u64 v[10:11], v[10:11], 0, v[2:3]
	v_lshl_add_u64 v[12:13], v[12:13], 4, s[8:9]
	v_lshl_add_u64 v[10:11], v[10:11], 4, s[8:9]
	global_load_dwordx4 v[46:49], v[12:13], off sc1
	global_load_dwordx4 v[50:53], v[10:11], off sc1
	s_add_i32 s13, s13, s56
	s_cmpk_gt_i32 s13, 0x1ff
	s_cbranch_scc1 .Lrsb_PLE1_p2
	s_ashr_i32 s4, s13, 31
	s_lshr_b32 s4, s4, 29
	s_add_i32 s4, s13, s4
	s_ashr_i32 s5, s4, 3
	s_and_b32 s4, s4, -8
	s_sub_i32 s4, s13, s4
	s_lshr_b32 s10, s4, 31
	s_or_b32 s10, s10, 64
	s_mul_i32 s4, s10, s4
	s_add_i32 s4, s4, s5
	s_ashr_i32 s5, s4, 31
	s_lshr_b32 s5, s5, 27
	s_add_i32 s5, s4, s5
	s_ashr_i32 s10, s5, 5
	s_lshl_b32 s10, s10, 3
	s_sub_i32 s11, 0x80, s10
	s_min_u32 s11, s11, 8
	s_andn2_b32 s5, s5, 31
	s_sub_i32 s14, s4, s5
	s_waitcnt lgkmcnt(0)
	v_cvt_f32_ubyte0_e32 v11, s11
	v_cvt_f32_i32_e32 v10, s14
	v_rcp_iflag_f32_e32 v12, v11
	s_ashr_i32 s4, s14, 30
	s_or_b32 s15, s4, 1
	v_mul_f32_e32 v12, v10, v12
	v_trunc_f32_e32 v12, v12
	v_fma_f32 v10, -v12, v11, v10
	v_cvt_i32_f32_e32 v12, v12
	v_cmp_ge_f32_e64 s[4:5], |v10|, v11
	s_and_b64 s[4:5], s[4:5], exec
	s_cselect_b32 s4, s15, 0
	v_readfirstlane_b32 s5, v12
	s_add_i32 s4, s5, s4
	s_mul_i32 s4, s4, s11
	s_sub_i32 s4, s14, s4
	s_sext_i32_i8 s4, s4
	s_add_i32 s10, s10, s4
	v_lshl_add_u32 v10, s10, 8, v8
	v_ashrrev_i32_e32 v11, 31, v10
	v_lshl_add_u64 v[12:13], v[10:11], 0, v[0:1]
	v_lshl_add_u64 v[10:11], v[10:11], 0, v[2:3]
	v_lshl_add_u64 v[12:13], v[12:13], 4, s[8:9]
	v_lshl_add_u64 v[10:11], v[10:11], 4, s[8:9]
	global_load_dwordx4 v[54:57], v[12:13], off sc1
	global_load_dwordx4 v[58:61], v[10:11], off sc1
	s_add_i32 s13, s13, s56
	s_cmpk_gt_i32 s13, 0x1ff
	s_cbranch_scc1 .Lrsb_PLE1_p2
	s_ashr_i32 s4, s13, 31
	s_lshr_b32 s4, s4, 29
	s_add_i32 s4, s13, s4
	s_ashr_i32 s5, s4, 3
	s_and_b32 s4, s4, -8
	s_sub_i32 s4, s13, s4
	s_lshr_b32 s10, s4, 31
	s_or_b32 s10, s10, 64
	s_mul_i32 s4, s10, s4
	s_add_i32 s4, s4, s5
	s_ashr_i32 s5, s4, 31
	s_lshr_b32 s5, s5, 27
	s_add_i32 s5, s4, s5
	s_ashr_i32 s10, s5, 5
	s_lshl_b32 s10, s10, 3
	s_sub_i32 s11, 0x80, s10
	s_min_u32 s11, s11, 8
	s_andn2_b32 s5, s5, 31
	s_sub_i32 s14, s4, s5
	s_waitcnt lgkmcnt(0)
	v_cvt_f32_ubyte0_e32 v11, s11
	v_cvt_f32_i32_e32 v10, s14
	v_rcp_iflag_f32_e32 v12, v11
	s_ashr_i32 s4, s14, 30
	s_or_b32 s15, s4, 1
	v_mul_f32_e32 v12, v10, v12
	v_trunc_f32_e32 v12, v12
	v_fma_f32 v10, -v12, v11, v10
	v_cvt_i32_f32_e32 v12, v12
	v_cmp_ge_f32_e64 s[4:5], |v10|, v11
	s_and_b64 s[4:5], s[4:5], exec
	s_cselect_b32 s4, s15, 0
	v_readfirstlane_b32 s5, v12
	s_add_i32 s4, s5, s4
	s_mul_i32 s4, s4, s11
	s_sub_i32 s4, s14, s4
	s_sext_i32_i8 s4, s4
	s_add_i32 s10, s10, s4
	v_lshl_add_u32 v10, s10, 8, v8
	v_ashrrev_i32_e32 v11, 31, v10
	v_lshl_add_u64 v[12:13], v[10:11], 0, v[0:1]
	v_lshl_add_u64 v[10:11], v[10:11], 0, v[2:3]
	v_lshl_add_u64 v[12:13], v[12:13], 4, s[8:9]
	v_lshl_add_u64 v[10:11], v[10:11], 4, s[8:9]
	global_load_dwordx4 v[62:65], v[12:13], off sc1
	global_load_dwordx4 v[66:69], v[10:11], off sc1
	s_add_i32 s13, s13, s56
	s_cmpk_gt_i32 s13, 0x1ff
	s_cbranch_scc1 .Lrsb_PLE1_p2
	s_ashr_i32 s4, s13, 31
	s_lshr_b32 s4, s4, 29
	s_add_i32 s4, s13, s4
	s_ashr_i32 s5, s4, 3
	s_and_b32 s4, s4, -8
	s_sub_i32 s4, s13, s4
	s_lshr_b32 s10, s4, 31
	s_or_b32 s10, s10, 64
	s_mul_i32 s4, s10, s4
	s_add_i32 s4, s4, s5
	s_ashr_i32 s5, s4, 31
	s_lshr_b32 s5, s5, 27
	s_add_i32 s5, s4, s5
	s_ashr_i32 s10, s5, 5
	s_lshl_b32 s10, s10, 3
	s_sub_i32 s11, 0x80, s10
	s_min_u32 s11, s11, 8
	s_andn2_b32 s5, s5, 31
	s_sub_i32 s14, s4, s5
	s_waitcnt lgkmcnt(0)
	v_cvt_f32_ubyte0_e32 v11, s11
	v_cvt_f32_i32_e32 v10, s14
	v_rcp_iflag_f32_e32 v12, v11
	s_ashr_i32 s4, s14, 30
	s_or_b32 s15, s4, 1
	v_mul_f32_e32 v12, v10, v12
	v_trunc_f32_e32 v12, v12
	v_fma_f32 v10, -v12, v11, v10
	v_cvt_i32_f32_e32 v12, v12
	v_cmp_ge_f32_e64 s[4:5], |v10|, v11
	s_and_b64 s[4:5], s[4:5], exec
	s_cselect_b32 s4, s15, 0
	v_readfirstlane_b32 s5, v12
	s_add_i32 s4, s5, s4
	s_mul_i32 s4, s4, s11
	s_sub_i32 s4, s14, s4
	s_sext_i32_i8 s4, s4
	s_add_i32 s10, s10, s4
	v_lshl_add_u32 v10, s10, 8, v8
	v_ashrrev_i32_e32 v11, 31, v10
	v_lshl_add_u64 v[12:13], v[10:11], 0, v[0:1]
	v_lshl_add_u64 v[10:11], v[10:11], 0, v[2:3]
	v_lshl_add_u64 v[12:13], v[12:13], 4, s[8:9]
	v_lshl_add_u64 v[10:11], v[10:11], 4, s[8:9]
	global_load_dwordx4 v[70:73], v[12:13], off sc1
	global_load_dwordx4 v[74:77], v[10:11], off sc1
	s_add_i32 s13, s13, s56
	s_cmpk_gt_i32 s13, 0x1ff
	s_cbranch_scc1 .Lrsb_PLE1_p2
; template <int PH, int SUB> __device__ __forceinline__ void rs_fill(LAS unsigned char* lds, const Epi& E) {
;     ...
;         for (int i = 0; i < 12; ++i) { Unit u; if (!sched_next<PH, SUB>(E.ws, E.layer, i, u)) break;
;             const int r = tidx >> 1, hf = tidx & 1; const size_t row = (size_t)(u.pm * 256 + r); f32x4 a, b;
;             { unsigned* pa = (unsigned*)(ssq + ((size_t)(2 * hf) * T_TOK + row) * 4); unsigned* pb = (unsigned*)(ssq + ((size_t)(2 * hf + 1) * T_TOK + row) * 4);
; #pragma unroll
;               for (int j = 0; j < 4; ++j) { a[j] = __uint_as_float(__hip_atomic_load(pa + j, __ATOMIC_RELAXED, __HIP_MEMORY_SCOPE_AGENT)); b[j] = __uint_as_float(__hip_atomic_load(pb + j, __ATOMIC_RELAXED, __HIP_MEMORY_SCOPE_AGENT)); } }
	s_ashr_i32 s4, s13, 31
	s_lshr_b32 s4, s4, 29
	s_add_i32 s4, s13, s4
	s_ashr_i32 s5, s4, 3
	s_and_b32 s4, s4, -8
	s_sub_i32 s4, s13, s4
	s_lshr_b32 s10, s4, 31
	s_or_b32 s10, s10, 64
	s_mul_i32 s4, s10, s4
	s_add_i32 s4, s4, s5
	s_ashr_i32 s5, s4, 31
	s_lshr_b32 s5, s5, 27
	s_add_i32 s5, s4, s5
	s_ashr_i32 s10, s5, 5
	s_lshl_b32 s10, s10, 3
	s_sub_i32 s11, 0x80, s10
	s_min_u32 s11, s11, 8
	s_andn2_b32 s5, s5, 31
	s_sub_i32 s14, s4, s5
	s_waitcnt lgkmcnt(0)
	v_cvt_f32_ubyte0_e32 v11, s11
	v_cvt_f32_i32_e32 v10, s14
	v_rcp_iflag_f32_e32 v12, v11
	s_ashr_i32 s4, s14, 30
	s_or_b32 s15, s4, 1
	v_mul_f32_e32 v12, v10, v12
	v_trunc_f32_e32 v12, v12
	v_fma_f32 v10, -v12, v11, v10
	v_cvt_i32_f32_e32 v12, v12
	v_cmp_ge_f32_e64 s[4:5], |v10|, v11
	s_and_b64 s[4:5], s[4:5], exec
	s_cselect_b32 s4, s15, 0
	v_readfirstlane_b32 s5, v12
	s_add_i32 s4, s5, s4
	s_mul_i32 s4, s4, s11
	s_sub_i32 s4, s14, s4
	s_sext_i32_i8 s4, s4
	s_add_i32 s10, s10, s4
	v_lshl_add_u32 v10, s10, 8, v8
	v_ashrrev_i32_e32 v11, 31, v10
	v_lshl_add_u64 v[12:13], v[10:11], 0, v[0:1]
	v_lshl_add_u64 v[10:11], v[10:11], 0, v[2:3]
	v_lshl_add_u64 v[12:13], v[12:13], 4, s[8:9]
	v_lshl_add_u64 v[10:11], v[10:11], 4, s[8:9]
	global_load_dwordx4 v[78:81], v[12:13], off sc1
	global_load_dwordx4 v[82:85], v[10:11], off sc1
	s_add_i32 s13, s13, s56
	s_cmpk_gt_i32 s13, 0x1ff
	s_cbranch_scc1 .Lrsb_PLE1_p2
	s_ashr_i32 s4, s13, 31
	s_lshr_b32 s4, s4, 29
	s_add_i32 s4, s13, s4
	s_ashr_i32 s5, s4, 3
	s_and_b32 s4, s4, -8
	s_sub_i32 s4, s13, s4
	s_lshr_b32 s10, s4, 31
	s_or_b32 s10, s10, 64
	s_mul_i32 s4, s10, s4
	s_add_i32 s4, s4, s5
	s_ashr_i32 s5, s4, 31
	s_lshr_b32 s5, s5, 27
	s_add_i32 s5, s4, s5
	s_ashr_i32 s10, s5, 5
	s_lshl_b32 s10, s10, 3
	s_sub_i32 s11, 0x80, s10
	s_min_u32 s11, s11, 8
	s_andn2_b32 s5, s5, 31
	s_sub_i32 s14, s4, s5
	s_waitcnt lgkmcnt(0)
	v_cvt_f32_ubyte0_e32 v11, s11
	v_cvt_f32_i32_e32 v10, s14
	v_rcp_iflag_f32_e32 v12, v11
	s_ashr_i32 s4, s14, 30
	s_or_b32 s15, s4, 1
	v_mul_f32_e32 v12, v10, v12
	v_trunc_f32_e32 v12, v12
	v_fma_f32 v10, -v12, v11, v10
	v_cvt_i32_f32_e32 v12, v12
	v_cmp_ge_f32_e64 s[4:5], |v10|, v11
	s_and_b64 s[4:5], s[4:5], exec
	s_cselect_b32 s4, s15, 0
	v_readfirstlane_b32 s5, v12
	s_add_i32 s4, s5, s4
	s_mul_i32 s4, s4, s11
	s_sub_i32 s4, s14, s4
	s_sext_i32_i8 s4, s4
	s_add_i32 s10, s10, s4
	v_lshl_add_u32 v10, s10, 8, v8
	v_ashrrev_i32_e32 v11, 31, v10
	v_lshl_add_u64 v[12:13], v[10:11], 0, v[0:1]
	v_lshl_add_u64 v[10:11], v[10:11], 0, v[2:3]
	v_lshl_add_u64 v[12:13], v[12:13], 4, s[8:9]
	v_lshl_add_u64 v[10:11], v[10:11], 4, s[8:9]
	global_load_dwordx4 v[86:89], v[12:13], off sc1
	global_load_dwordx4 v[90:93], v[10:11], off sc1
	s_add_i32 s13, s13, s56
	s_cmpk_gt_i32 s13, 0x1ff
	s_cbranch_scc1 .Lrsb_PLE1_p2
	s_ashr_i32 s4, s13, 31
	s_lshr_b32 s4, s4, 29
	s_add_i32 s4, s13, s4
	s_ashr_i32 s5, s4, 3
	s_and_b32 s4, s4, -8
	s_sub_i32 s4, s13, s4
	s_lshr_b32 s10, s4, 31
	s_or_b32 s10, s10, 64
	s_mul_i32 s4, s10, s4
	s_add_i32 s4, s4, s5
	s_ashr_i32 s5, s4, 31
	s_lshr_b32 s5, s5, 27
	s_add_i32 s5, s4, s5
	s_ashr_i32 s10, s5, 5
	s_lshl_b32 s10, s10, 3
	s_sub_i32 s11, 0x80, s10
	s_min_u32 s11, s11, 8
	s_andn2_b32 s5, s5, 31
	s_sub_i32 s14, s4, s5
	s_waitcnt lgkmcnt(0)
	v_cvt_f32_ubyte0_e32 v11, s11
	v_cvt_f32_i32_e32 v10, s14
	v_rcp_iflag_f32_e32 v12, v11
	s_ashr_i32 s4, s14, 30
	s_or_b32 s15, s4, 1
	v_mul_f32_e32 v12, v10, v12
	v_trunc_f32_e32 v12, v12
	v_fma_f32 v10, -v12, v11, v10
	v_cvt_i32_f32_e32 v12, v12
	v_cmp_ge_f32_e64 s[4:5], |v10|, v11
	s_and_b64 s[4:5], s[4:5], exec
	s_cselect_b32 s4, s15, 0
	v_readfirstlane_b32 s5, v12
	s_add_i32 s4, s5, s4
	s_mul_i32 s4, s4, s11
	s_sub_i32 s4, s14, s4
	s_sext_i32_i8 s4, s4
	s_add_i32 s10, s10, s4
	v_lshl_add_u32 v10, s10, 8, v8
	v_ashrrev_i32_e32 v11, 31, v10
	v_lshl_add_u64 v[12:13], v[10:11], 0, v[0:1]
	v_lshl_add_u64 v[10:11], v[10:11], 0, v[2:3]
	v_lshl_add_u64 v[12:13], v[12:13], 4, s[8:9]
	v_lshl_add_u64 v[10:11], v[10:11], 4, s[8:9]
	global_load_dwordx4 v[94:97], v[12:13], off sc1
	global_load_dwordx4 v[98:101], v[10:11], off sc1
	s_add_i32 s13, s13, s56
	s_cmpk_gt_i32 s13, 0x1ff
	s_cbranch_scc1 .Lrsb_PLE1_p2
	s_ashr_i32 s4, s13, 31
	s_lshr_b32 s4, s4, 29
	s_add_i32 s4, s13, s4
	s_ashr_i32 s5, s4, 3
	s_and_b32 s4, s4, -8
	s_sub_i32 s4, s13, s4
	s_lshr_b32 s10, s4, 31
	s_or_b32 s10, s10, 64
	s_mul_i32 s4, s10, s4
	s_add_i32 s4, s4, s5
	s_ashr_i32 s5, s4, 31
	s_lshr_b32 s5, s5, 27
	s_add_i32 s5, s4, s5
	s_ashr_i32 s10, s5, 5
	s_lshl_b32 s10, s10, 3
	s_sub_i32 s11, 0x80, s10
	s_min_u32 s11, s11, 8
	s_andn2_b32 s5, s5, 31
	s_sub_i32 s14, s4, s5
	s_waitcnt lgkmcnt(0)
	v_cvt_f32_ubyte0_e32 v11, s11
	v_cvt_f32_i32_e32 v10, s14
	v_rcp_iflag_f32_e32 v12, v11
	s_ashr_i32 s4, s14, 30
	s_or_b32 s15, s4, 1
	v_mul_f32_e32 v12, v10, v12
	v_trunc_f32_e32 v12, v12
	v_fma_f32 v10, -v12, v11, v10
	v_cvt_i32_f32_e32 v12, v12
	v_cmp_ge_f32_e64 s[4:5], |v10|, v11
	s_and_b64 s[4:5], s[4:5], exec
	s_cselect_b32 s4, s15, 0
	v_readfirstlane_b32 s5, v12
	s_add_i32 s4, s5, s4
	s_mul_i32 s4, s4, s11
	s_sub_i32 s4, s14, s4
	s_sext_i32_i8 s4, s4
	s_add_i32 s10, s10, s4
	v_lshl_add_u32 v10, s10, 8, v8
	v_ashrrev_i32_e32 v11, 31, v10
	v_lshl_add_u64 v[12:13], v[10:11], 0, v[0:1]
	v_lshl_add_u64 v[10:11], v[10:11], 0, v[2:3]
	v_lshl_add_u64 v[12:13], v[12:13], 4, s[8:9]
	v_lshl_add_u64 v[10:11], v[10:11], 4, s[8:9]
	global_load_dwordx4 v[102:105], v[12:13], off sc1
	global_load_dwordx4 v[106:109], v[10:11], off sc1
	s_add_i32 s13, s13, s56
